# launch-token broadcast replaces cooperative-groups grid sync; P3 group loads hoisted; P5 row-sum LDS table
# speedup vs baseline: 1.0336x; 1.0112x over previous
.LBB0_13:
	v_lshrrev_b32_e32 v1, 20, v0
	v_lshrrev_b32_e32 v0, 10, v0
	v_or_b32_e32 v0, v0, v1
	s_movk_i32 s4, 0x3ff
	v_and_or_b32 v0, v0, s4, v196
	v_cmp_eq_u32_e32 vcc, 0, v0
	s_waitcnt vmcnt(0)
	s_barrier
	s_and_saveexec_b64 s[4:5], vcc
	s_cbranch_execz .LBB0_23
	s_load_dwordx2 s[98:99], s[6:7], 0x58
	s_cmp_lg_u32 s2, 0
	s_cbranch_scc1 .LBB0_23
	buffer_wbl2 sc1
	s_waitcnt lgkmcnt(0)
	s_load_dword s100, s[98:99], 0x20
	s_waitcnt vmcnt(0) lgkmcnt(0)
	s_mul_i32 s8, s100, 0x9e3779b1
	s_add_i32 s8, s8, 0x7f4a7c15
	v_mov_b32_e32 v0, 0x7800
	v_mov_b32_e32 v1, s8
	global_store_dword v0, v1, s[70:71] sc0 sc1
.LBB0_23:
	s_or_b64 exec, exec, s[4:5]
	s_getreg_b32 s4, hwreg(HW_REG_XCC_ID, 0, 4)
	s_and_b32 s33, s4, 15
	s_add_i32 s94, 0, 0x23fa0

.LBB0_106:
	s_cmp_gt_i32 s29, 1
	s_cselect_b64 s[4:5], -1, 0
	s_and_b64 s[0:1], s[72:73], s[4:5]
	s_andn2_b64 vcc, exec, s[0:1]
	v_cmp_eq_u32_e64 s[0:1], 0, v196
	s_cbranch_vccnz .LBB0_156
	s_waitcnt vmcnt(0)
	s_waitcnt lgkmcnt(0)
	s_barrier
	s_and_saveexec_b64 s[6:7], s[0:1]
	s_cbranch_execz .LBB0_155
	s_load_dword s100, s[98:99], 0x20
	s_waitcnt lgkmcnt(0)
	s_mul_i32 s101, s100, 0x9e3779b1
	s_add_i32 s101, s101, 0x7f4a7c15
	v_mov_b32_e32 v0, 0x7800
	s_mov_b32 s8, 0
.Ltok_loop:
	global_load_dword v2, v0, s[70:71] sc1
	s_waitcnt vmcnt(0)
	v_cmp_eq_u32_e32 vcc, s101, v2
	s_cbranch_vccnz .Ltok_done
	s_add_i32 s8, s8, 1
	s_cmp_gt_u32 s8, 0x200000
	s_cbranch_scc1 .Ltok_done
	s_sleep 2
	s_branch .Ltok_loop
.Ltok_done:
	buffer_inv sc1
	s_lshl_b32 s8, s33, 8
	v_mov_b32_e32 v0, s8
	v_mov_b32_e32 v1, 1
	global_atomic_add v0, v1, s[92:93] offset:1024
	v_mov_b32_e32 v0, s94
	s_waitcnt vmcnt(0) expcnt(0) lgkmcnt(0)
	ds_read_b32 v2, v0
	ds_read_b32 v0, v0 offset:4
	s_waitcnt lgkmcnt(1)
	v_cmp_ne_u32_e32 vcc, 0, v2
	s_cbranch_vccnz .LBB0_123
	s_add_u32 s0, s70, 0x4200
	s_addc_u32 s1, s71, 0
	s_add_u32 s8, s70, 0x4400
	s_addc_u32 s9, s71, 0
	s_add_u32 s12, s70, 0x4500
	s_addc_u32 s13, s71, 0
	s_add_u32 s14, s70, 0x4600
	s_addc_u32 s15, s71, 0
	s_add_u32 s16, s70, 0x4700
	s_addc_u32 s17, s71, 0
	s_add_u32 s18, s70, 0x4800
	s_addc_u32 s19, s71, 0
	s_add_u32 s20, s70, 0x4900
	s_addc_u32 s21, s71, 0
	s_add_u32 s26, s70, 0x4a00
	s_addc_u32 s27, s71, 0
	s_add_u32 s36, s70, 0x4b00
	s_addc_u32 s37, s71, 0
	s_add_u32 s38, s70, 0x4c00
	s_addc_u32 s39, s71, 0
	s_add_u32 s40, s70, 0x4d00
	s_addc_u32 s41, s71, 0
	s_add_u32 s42, s70, 0x4e00
	s_addc_u32 s43, s71, 0
	s_add_u32 s44, s70, 0x4f00
	s_addc_u32 s45, s71, 0
	s_add_u32 s48, s70, 0x5000
	s_addc_u32 s49, s71, 0
	s_add_u32 s52, s70, 0x5100
	s_addc_u32 s53, s71, 0
	s_add_u32 s54, s70, 0x5200
	s_addc_u32 s55, s71, 0
	s_mul_i32 s3, s31, s95
	s_add_u32 s56, s70, 0x5300
	s_mul_i32 s3, s3, s30
	s_addc_u32 s57, s71, 0
	s_mov_b32 s10, 1
	v_mov_b32_e32 v16, 0
	s_branch .LBB0_111

.LBB0_405:
	s_or_b32 s10, s40, s18
	v_lshl_or_b32 v0, s10, 7, v129
	v_ashrrev_i32_e32 v1, 31, v0
	v_lshl_add_u64 v[0:1], v[0:1], 2, s[16:17]
	global_load_dwordx2 v[114:115], v[0:1], off
	global_load_dwordx2 v[112:113], v[0:1], off offset:256
	s_lshl_b32 s14, s10, 2
	s_lshl_b64 s[38:39], s[14:15], 10
	v_cndmask_b32_e64 v232, v194, v120, s[6:7]
	v_cndmask_b32_e64 v233, v195, v121, s[6:7]
	v_cndmask_b32_e64 v234, v198, v122, s[6:7]
	v_cndmask_b32_e64 v235, v199, v123, s[6:7]
	s_mov_b32 s40, 2
	s_and_b64 vcc, exec, s[6:7]
	s_waitcnt vmcnt(1)
	v_pk_mul_f32 v[2:3], v[114:115], v[114:115]
	s_nop 0
	v_sub_f32_e32 v2, v2, v3
	v_add_f32_e32 v3, v114, v114
	v_mul_f32_e32 v3, v115, v3
	v_mul_f32_e32 v4, v2, v2
	v_add_f32_e32 v2, v2, v2
	v_mul_f32_e32 v2, v3, v2
	v_fma_f32 v4, -v3, v3, v4
	v_mul_f32_e32 v3, v2, v2
	v_fma_f32 v3, v4, v4, -v3
	v_add_f32_e32 v4, v4, v4
	v_mul_f32_e32 v2, v2, v4
	v_mul_f32_e32 v4, v2, v2
	s_waitcnt vmcnt(0)
	v_pk_mul_f32 v[0:1], v[112:113], v[112:113]
	v_fma_f32 v230, v3, v3, -v4
	v_add_f32_e32 v3, v3, v3
	v_sub_f32_e32 v0, v0, v1
	v_add_f32_e32 v1, v112, v112
	v_mul_f32_e32 v231, v2, v3
	v_mul_f32_e32 v1, v113, v1
	v_mul_f32_e32 v2, v0, v0
	v_add_f32_e32 v0, v0, v0
	v_mul_f32_e32 v0, v1, v0
	v_fma_f32 v2, -v1, v1, v2
	v_mul_f32_e32 v1, v0, v0
	v_fma_f32 v1, v2, v2, -v1
	v_add_f32_e32 v2, v2, v2
	v_mul_f32_e32 v0, v0, v2
	v_mul_f32_e32 v2, v0, v0
	v_fma_f32 v228, v1, v1, -v2
	v_add_f32_e32 v1, v1, v1
	v_mul_f32_e32 v229, v0, v1
	v_lshl_add_u64 v[0:1], v[134:135], 0, s[38:39]
	s_or_b32 s38, s14, 1
	s_mov_b32 s39, s15
	s_lshl_b64 s[38:39], s[38:39], 10
	global_load_dwordx4 v[84:87], v[0:1], off
	v_lshl_add_u64 v[0:1], v[134:135], 0, s[38:39]
	s_or_b32 s38, s14, 2
	s_mov_b32 s39, s15
	s_lshl_b64 s[38:39], s[38:39], 10
	s_or_b32 s14, s14, 3
	global_load_dwordx4 v[88:91], v[0:1], off
	v_lshl_add_u64 v[0:1], v[134:135], 0, s[38:39]
	s_lshl_b64 s[38:39], s[14:15], 10
	s_lshl_b32 s14, s10, 4
	global_load_dwordx4 v[92:95], v[0:1], off
	v_lshl_add_u64 v[0:1], v[134:135], 0, s[38:39]
	v_or_b32_e32 v132, s14, v128
	global_load_dwordx4 v[96:99], v[0:1], off
	v_lshlrev_b64 v[0:1], 8, v[132:133]
	v_lshl_add_u64 v[0:1], v[138:139], 0, v[0:1]
	global_load_dwordx4 v[80:83], v[0:1], off
	global_load_dwordx4 v[76:79], v[0:1], off offset:64
	global_load_dwordx4 v[72:75], v[0:1], off offset:128
	global_load_dwordx4 v[68:71], v[0:1], off offset:192
	v_lshl_add_u64 v[0:1], s[14:15], 2, v[140:141]
	s_lshl_b32 s38, s10, 5
	s_mov_b32 s39, s15
	global_load_dwordx4 v[64:67], v[0:1], off
	v_lshl_add_u64 v[118:119], v[144:145], 0, s[38:39]
	v_or_b32_e32 v0, s14, v151
	v_lshl_add_u32 v132, v0, 1, s3
	v_lshl_add_u64 v[0:1], v[118:119], 0, v[100:101]
	global_load_dwordx4 v[0:3], v[0:1], off
	v_lshl_add_u64 v[116:117], v[146:147], 0, s[38:39]
	v_lshl_add_u64 v[244:245], v[118:119], 0, v[106:107]
	v_lshl_add_u64 v[248:249], v[116:117], 0, v[102:103]
	v_lshl_add_u64 v[250:251], v[116:117], 0, v[104:105]
	v_lshl_add_u64 v[252:253], v[116:117], 0, v[108:109]
	v_lshl_add_u64 v[242:243], v[116:117], 0, v[110:111]
	global_load_dwordx4 v[244:247], v[244:245], off
	global_load_dwordx2 v[248:249], v[248:249], off
	global_load_dwordx2 v[250:251], v[250:251], off
	global_load_dwordx2 v[252:253], v[252:253], off
	global_load_dwordx2 v[242:243], v[242:243], off
	s_or_b32 s38, s10, 1
	s_lshl_b32 s14, s38, 2
	s_lshl_b64 s[10:11], s[14:15], 10
	s_waitcnt vmcnt(0)
	v_mfma_f32_32x32x16_bf16 v[32:47], v[0:3], v[92:95], 0
	s_nop 11
	v_fma_f32 v237, 0, v115, v32
	v_mfma_f32_32x32x16_bf16 v[48:63], v[0:3], v[84:87], 0
	v_fmac_f32_e32 v237, 0, v114
	v_mfma_f32_32x32x16_bf16 v[16:31], v[0:3], v[88:91], 0
	s_nop 9
	v_fmamk_f32 v236, v115, 0x80000000, v48
	v_fmac_f32_e32 v236, 0, v114
	v_fma_f32 v238, -v115, v237, v49
	v_fmac_f32_e32 v238, v114, v236
	v_fma_f32 v236, v115, v236, v33
	v_fmac_f32_e32 v236, v114, v237
	v_fma_f32 v237, -v115, v236, v50
	v_fmac_f32_e32 v237, v114, v238
	v_fma_f32 v238, v115, v238, v34
	v_fmac_f32_e32 v238, v114, v236
	v_fma_f32 v236, -v115, v238, v51
	v_fmac_f32_e32 v236, v114, v237
	v_fma_f32 v237, v115, v237, v35
	v_fmac_f32_e32 v237, v114, v238
	v_fma_f32 v238, -v115, v237, v52
	v_fmac_f32_e32 v238, v114, v236
	v_fma_f32 v236, v115, v236, v36
	v_fmac_f32_e32 v236, v114, v237
	v_fma_f32 v237, -v115, v236, v53
	v_fmac_f32_e32 v237, v114, v238
	v_fma_f32 v238, v115, v238, v37
	v_fmac_f32_e32 v238, v114, v236
	v_fma_f32 v236, -v115, v238, v54
	v_fmac_f32_e32 v236, v114, v237
	v_fma_f32 v237, v115, v237, v38
	v_fmac_f32_e32 v237, v114, v238
	v_fma_f32 v238, -v115, v237, v55
	v_fmac_f32_e32 v238, v114, v236
	v_fma_f32 v236, v115, v236, v39
	v_fmac_f32_e32 v236, v114, v237
	v_fma_f32 v237, -v115, v236, v56
	v_fmac_f32_e32 v237, v114, v238
	v_fma_f32 v238, v115, v238, v40
	v_fmac_f32_e32 v238, v114, v236
	v_fma_f32 v236, -v115, v238, v57
	v_fmac_f32_e32 v236, v114, v237
	v_fma_f32 v237, v115, v237, v41
	v_fmac_f32_e32 v237, v114, v238
	v_fma_f32 v238, -v115, v237, v58
	v_fmac_f32_e32 v238, v114, v236
	v_fma_f32 v236, v115, v236, v42
	v_fmac_f32_e32 v236, v114, v237
	v_fma_f32 v237, -v115, v236, v59
	v_fmac_f32_e32 v237, v114, v238
	v_fma_f32 v238, v115, v238, v43
	v_fmac_f32_e32 v238, v114, v236
	v_fma_f32 v236, -v115, v238, v60
	v_fmac_f32_e32 v236, v114, v237
	v_fma_f32 v237, v115, v237, v44
	v_fmac_f32_e32 v237, v114, v238
	v_fma_f32 v238, -v115, v237, v61
	v_fmac_f32_e32 v238, v114, v236
	v_fma_f32 v236, v115, v236, v45
	v_fmac_f32_e32 v236, v114, v237
	v_fma_f32 v237, -v115, v236, v62
	v_fmac_f32_e32 v237, v114, v238
	v_fma_f32 v238, v115, v238, v46
	v_fmac_f32_e32 v238, v114, v236
	v_fma_f32 v236, -v115, v238, v63
	v_fmac_f32_e32 v236, v114, v237
	v_fma_f32 v237, v115, v237, v47
	v_fmac_f32_e32 v237, v114, v238
	ds_bpermute_b32 v238, v149, v236
	ds_bpermute_b32 v239, v149, v237
	v_mfma_f32_32x32x16_bf16 v[0:15], v[0:3], v[96:99], 0
	s_waitcnt lgkmcnt(1)
	v_cndmask_b32_e64 v240, v238, v236, s[0:1]
	s_waitcnt lgkmcnt(0)
	v_cndmask_b32_e64 v241, v239, v237, s[0:1]
	v_cndmask_b32_e64 v236, v236, v238, s[0:1]
	v_fma_f32 v238, -v231, v233, v240
	v_fmac_f32_e32 v241, v231, v232
	v_fmac_f32_e32 v238, v230, v232
	v_fmac_f32_e32 v241, v230, v233
	v_cndmask_b32_e64 v232, v238, v232, s[0:1]
	v_cndmask_b32_e64 v233, v241, v233, s[0:1]
	v_fma_f32 v48, -v115, v233, v48
	v_fma_f32 v32, v115, v232, v32
	v_fmac_f32_e32 v48, v114, v232
	v_fmac_f32_e32 v32, v114, v233
	v_fma_f32 v49, -v115, v32, v49
	v_fma_f32 v33, v115, v48, v33
	v_cvt_pk_bf16_f32 v232, v48, v32
	ds_write_b32 v137, v232
	v_fmac_f32_e32 v49, v114, v48
	v_fmac_f32_e32 v33, v114, v32
	v_cvt_pk_bf16_f32 v32, v49, v33
	ds_write_b32 v137, v32 offset:272
	v_fma_f32 v32, -v115, v33, v50
	v_fma_f32 v34, v115, v49, v34
	v_fmac_f32_e32 v32, v114, v49
	v_fmac_f32_e32 v34, v114, v33
	v_cvt_pk_bf16_f32 v33, v32, v34
	ds_write_b32 v137, v33 offset:544
	v_fma_f32 v33, -v115, v34, v51
	v_fmac_f32_e32 v33, v114, v32
	v_fma_f32 v32, v115, v32, v35
	v_fmac_f32_e32 v32, v114, v34
	v_cvt_pk_bf16_f32 v34, v33, v32
	ds_write_b32 v137, v34 offset:816
	v_fma_f32 v34, -v115, v32, v52
	v_fmac_f32_e32 v34, v114, v33
	v_fma_f32 v33, v115, v33, v36
	v_fmac_f32_e32 v33, v114, v32
	v_cvt_pk_bf16_f32 v32, v34, v33
	ds_write_b32 v137, v32 offset:1088
	v_fma_f32 v32, -v115, v33, v53
	v_fmac_f32_e32 v32, v114, v34
	v_fma_f32 v34, v115, v34, v37
	v_fmac_f32_e32 v34, v114, v33
	v_cvt_pk_bf16_f32 v33, v32, v34
	ds_write_b32 v137, v33 offset:1360
	v_fma_f32 v33, -v115, v34, v54
	v_fmac_f32_e32 v33, v114, v32
	v_fma_f32 v32, v115, v32, v38
	v_fmac_f32_e32 v32, v114, v34
	v_cvt_pk_bf16_f32 v34, v33, v32
	ds_write_b32 v137, v34 offset:1632
	v_fma_f32 v34, -v115, v32, v55
	v_fmac_f32_e32 v34, v114, v33
	v_fma_f32 v33, v115, v33, v39
	v_fmac_f32_e32 v33, v114, v32
	v_cvt_pk_bf16_f32 v32, v34, v33
	ds_write_b32 v137, v32 offset:1904
	v_fma_f32 v32, -v115, v33, v56
	v_fmac_f32_e32 v32, v114, v34
	v_fma_f32 v34, v115, v34, v40
	v_fmac_f32_e32 v34, v114, v33
	v_cvt_pk_bf16_f32 v33, v32, v34
	ds_write_b32 v137, v33 offset:2176
	v_fma_f32 v33, -v115, v34, v57
	v_fmac_f32_e32 v33, v114, v32
	v_fma_f32 v32, v115, v32, v41
	v_fmac_f32_e32 v32, v114, v34
	v_cvt_pk_bf16_f32 v34, v33, v32
	ds_write_b32 v137, v34 offset:2448
	v_fma_f32 v34, -v115, v32, v58
	v_fmac_f32_e32 v34, v114, v33
	v_fma_f32 v33, v115, v33, v42
	v_fmac_f32_e32 v33, v114, v32
	v_cvt_pk_bf16_f32 v32, v34, v33
	ds_write_b32 v137, v32 offset:2720
	v_fma_f32 v32, -v115, v33, v59
	v_fmac_f32_e32 v32, v114, v34
	v_fma_f32 v34, v115, v34, v43
	v_fmac_f32_e32 v34, v114, v33
	v_cvt_pk_bf16_f32 v33, v32, v34
	ds_write_b32 v137, v33 offset:2992
	v_fma_f32 v33, -v115, v34, v60
	v_fmac_f32_e32 v33, v114, v32
	v_fma_f32 v32, v115, v32, v44
	v_fmac_f32_e32 v32, v114, v34
	v_cvt_pk_bf16_f32 v34, v33, v32
	ds_write_b32 v137, v34 offset:3264
	v_fma_f32 v34, -v115, v32, v61
	v_fmac_f32_e32 v34, v114, v33
	v_fma_f32 v33, v115, v33, v45
	v_fmac_f32_e32 v33, v114, v32
	v_cvt_pk_bf16_f32 v32, v34, v33
	ds_write_b32 v137, v32 offset:3536
	v_fma_f32 v32, -v115, v33, v62
	v_fmac_f32_e32 v32, v114, v34
	v_fma_f32 v34, v115, v34, v46
	v_fmac_f32_e32 v34, v114, v33
	v_cvt_pk_bf16_f32 v33, v32, v34
	ds_write_b32 v137, v33 offset:3808
	v_fma_f32 v33, -v115, v34, v63
	v_fmac_f32_e32 v33, v114, v32
	v_fmac_f32_e32 v47, v115, v32
	v_fmac_f32_e32 v47, v114, v34
	v_cvt_pk_bf16_f32 v32, v33, v47
	v_fma_f32 v33, 0, v113, v0
	ds_write_b32 v137, v32 offset:4080
	v_fmamk_f32 v32, v113, 0x80000000, v16
	v_fmac_f32_e32 v33, 0, v112
	v_fmac_f32_e32 v32, 0, v112
	v_fma_f32 v34, -v113, v33, v17
	v_fmac_f32_e32 v34, v112, v32
	v_fma_f32 v32, v113, v32, v1
	v_fmac_f32_e32 v32, v112, v33
	v_fma_f32 v33, -v113, v32, v18
	v_fmac_f32_e32 v33, v112, v34
	v_fma_f32 v34, v113, v34, v2
	v_fmac_f32_e32 v34, v112, v32
	v_fma_f32 v32, -v113, v34, v19
	v_fmac_f32_e32 v32, v112, v33
	v_fma_f32 v33, v113, v33, v3
	v_fmac_f32_e32 v33, v112, v34
	v_fma_f32 v34, -v113, v33, v20
	v_fmac_f32_e32 v34, v112, v32
	v_fma_f32 v32, v113, v32, v4
	v_fmac_f32_e32 v32, v112, v33
	v_fma_f32 v33, -v113, v32, v21
	v_fmac_f32_e32 v33, v112, v34
	v_fma_f32 v34, v113, v34, v5
	v_fmac_f32_e32 v34, v112, v32
	v_fma_f32 v32, -v113, v34, v22
	v_fmac_f32_e32 v32, v112, v33
	v_fma_f32 v33, v113, v33, v6
	v_fmac_f32_e32 v33, v112, v34
	v_fma_f32 v34, -v113, v33, v23
	v_fmac_f32_e32 v34, v112, v32
	v_fma_f32 v32, v113, v32, v7
	v_fmac_f32_e32 v32, v112, v33
	v_fma_f32 v33, -v113, v32, v24
	v_fmac_f32_e32 v33, v112, v34
	v_fma_f32 v34, v113, v34, v8
	v_fmac_f32_e32 v34, v112, v32
	v_fma_f32 v32, -v113, v34, v25
	v_fmac_f32_e32 v32, v112, v33
	v_fma_f32 v33, v113, v33, v9
	v_fmac_f32_e32 v33, v112, v34
	v_fma_f32 v34, -v113, v33, v26
	v_fmac_f32_e32 v34, v112, v32
	v_fma_f32 v32, v113, v32, v10
	v_fmac_f32_e32 v32, v112, v33
	v_fma_f32 v33, -v113, v32, v27
	v_fmac_f32_e32 v33, v112, v34
	v_fma_f32 v34, v113, v34, v11
	v_fmac_f32_e32 v34, v112, v32
	v_fma_f32 v32, -v113, v34, v28
	v_fmac_f32_e32 v32, v112, v33
	v_fma_f32 v33, v113, v33, v12
	v_fmac_f32_e32 v33, v112, v34
	v_fma_f32 v34, -v113, v33, v29
	v_fmac_f32_e32 v34, v112, v32
	v_fma_f32 v32, v113, v32, v13
	v_fmac_f32_e32 v32, v112, v33
	v_fma_f32 v33, -v113, v32, v30
	v_fmac_f32_e32 v33, v112, v34
	v_fma_f32 v34, v113, v34, v14
	v_fmac_f32_e32 v34, v112, v32
	v_fma_f32 v32, -v113, v34, v31
	v_fmac_f32_e32 v32, v112, v33
	v_fma_f32 v33, v113, v33, v15
	v_fmac_f32_e32 v33, v112, v34
	ds_bpermute_b32 v34, v149, v32
	ds_bpermute_b32 v35, v149, v33
	v_cndmask_b32_e64 v237, v237, v239, s[0:1]
	v_fma_f32 v236, -v231, v241, v236
	v_fmac_f32_e32 v237, v231, v238
	s_waitcnt lgkmcnt(1)
	v_cndmask_b32_e64 v36, v34, v32, s[0:1]
	s_waitcnt lgkmcnt(0)
	v_cndmask_b32_e64 v37, v35, v33, s[0:1]
	v_cndmask_b32_e64 v232, v33, v35, s[0:1]
	v_fma_f32 v33, -v229, v235, v36
	v_fmac_f32_e32 v37, v229, v234
	v_fmac_f32_e32 v33, v228, v234
	v_fmac_f32_e32 v37, v228, v235
	v_cndmask_b32_e64 v32, v32, v34, s[0:1]
	v_cndmask_b32_e64 v34, v33, v234, s[0:1]
	v_cndmask_b32_e64 v35, v37, v235, s[0:1]
	v_fma_f32 v16, -v113, v35, v16
	v_fma_f32 v0, v113, v34, v0
	v_fmac_f32_e32 v16, v112, v34
	v_fmac_f32_e32 v0, v112, v35
	v_fma_f32 v17, -v113, v0, v17
	v_fma_f32 v1, v113, v16, v1
	v_fma_f32 v233, -v229, v37, v32
	v_cvt_pk_bf16_f32 v32, v16, v0
	ds_write_b32 v137, v32 offset:128
	v_fmac_f32_e32 v17, v112, v16
	v_fmac_f32_e32 v1, v112, v0
	v_cvt_pk_bf16_f32 v0, v17, v1
	ds_write_b32 v137, v0 offset:400
	v_fma_f32 v0, -v113, v1, v18
	v_fma_f32 v2, v113, v17, v2
	v_fmac_f32_e32 v0, v112, v17
	v_fmac_f32_e32 v2, v112, v1
	v_cvt_pk_bf16_f32 v1, v0, v2
	ds_write_b32 v137, v1 offset:672
	v_fma_f32 v1, -v113, v2, v19
	v_fmac_f32_e32 v1, v112, v0
	v_fma_f32 v0, v113, v0, v3
	v_fmac_f32_e32 v0, v112, v2
	v_cvt_pk_bf16_f32 v2, v1, v0
	ds_write_b32 v137, v2 offset:944
	v_fma_f32 v2, -v113, v0, v20
	v_fmac_f32_e32 v2, v112, v1
	v_fma_f32 v1, v113, v1, v4
	v_fmac_f32_e32 v1, v112, v0
	v_cvt_pk_bf16_f32 v0, v2, v1
	ds_write_b32 v137, v0 offset:1216
	v_fma_f32 v0, -v113, v1, v21
	v_fmac_f32_e32 v0, v112, v2
	v_fma_f32 v2, v113, v2, v5
	v_fmac_f32_e32 v2, v112, v1
	v_cvt_pk_bf16_f32 v1, v0, v2
	ds_write_b32 v137, v1 offset:1488
	v_fma_f32 v1, -v113, v2, v22
	v_fmac_f32_e32 v1, v112, v0
	v_fma_f32 v0, v113, v0, v6
	v_fmac_f32_e32 v0, v112, v2
	v_cvt_pk_bf16_f32 v2, v1, v0
	ds_write_b32 v137, v2 offset:1760
	v_fma_f32 v2, -v113, v0, v23
	v_fmac_f32_e32 v2, v112, v1
	v_fma_f32 v1, v113, v1, v7
	v_fmac_f32_e32 v1, v112, v0
	v_cvt_pk_bf16_f32 v0, v2, v1
	ds_write_b32 v137, v0 offset:2032
	v_fma_f32 v0, -v113, v1, v24
	v_fmac_f32_e32 v0, v112, v2
	v_fma_f32 v2, v113, v2, v8
	v_fmac_f32_e32 v2, v112, v1
	v_cvt_pk_bf16_f32 v1, v0, v2
	ds_write_b32 v137, v1 offset:2304
	v_fma_f32 v1, -v113, v2, v25
	v_fmac_f32_e32 v1, v112, v0
	v_fma_f32 v0, v113, v0, v9
	v_fmac_f32_e32 v0, v112, v2
	v_cvt_pk_bf16_f32 v2, v1, v0
	ds_write_b32 v137, v2 offset:2576
	v_fma_f32 v2, -v113, v0, v26
	v_fmac_f32_e32 v2, v112, v1
	v_fma_f32 v1, v113, v1, v10
	v_fmac_f32_e32 v1, v112, v0
	v_cvt_pk_bf16_f32 v0, v2, v1
	ds_write_b32 v137, v0 offset:2848
	v_fma_f32 v0, -v113, v1, v27
	v_fmac_f32_e32 v0, v112, v2
	v_fma_f32 v2, v113, v2, v11
	v_fmac_f32_e32 v2, v112, v1
	v_cvt_pk_bf16_f32 v1, v0, v2
	ds_write_b32 v137, v1 offset:3120
	v_fma_f32 v1, -v113, v2, v28
	v_fmac_f32_e32 v1, v112, v0
	v_fma_f32 v0, v113, v0, v12
	v_fmac_f32_e32 v0, v112, v2
	v_cvt_pk_bf16_f32 v2, v1, v0
	ds_write_b32 v137, v2 offset:3392
	v_fma_f32 v2, -v113, v0, v29
	v_fmac_f32_e32 v2, v112, v1
	v_fma_f32 v1, v113, v1, v13
	v_fmac_f32_e32 v1, v112, v0
	v_cvt_pk_bf16_f32 v0, v2, v1
	ds_write_b32 v137, v0 offset:3664
	v_fma_f32 v0, -v113, v1, v30
	v_fmac_f32_e32 v0, v112, v2
	v_fma_f32 v2, v113, v2, v14
	v_fmac_f32_e32 v2, v112, v1
	v_cvt_pk_bf16_f32 v1, v0, v2
	ds_write_b32 v137, v1 offset:3936
	v_fma_f32 v1, -v113, v2, v31
	v_fmac_f32_e32 v15, v113, v0
	v_fmac_f32_e32 v1, v112, v0
	v_fmac_f32_e32 v15, v112, v2
	v_cvt_pk_bf16_f32 v0, v1, v15
	ds_write_b32 v137, v0 offset:4208
	ds_read_b128 v[0:3], v220
	ds_read_b128 v[4:7], v220 offset:64
	s_waitcnt lgkmcnt(1)
	v_mfma_f32_16x16x32_bf16 v[0:3], v[80:83], v[0:3], 0
	v_add_u32_e32 v234, v132, v153
	v_fmac_f32_e32 v232, v229, v33
	v_fmac_f32_e32 v233, v228, v33
	s_waitcnt lgkmcnt(0)
	v_mfma_f32_16x16x32_bf16 v[0:3], v[76:79], v[4:7], v[0:3]
	ds_read_b128 v[4:7], v220 offset:128
	v_fmac_f32_e32 v232, v228, v37
	v_fmac_f32_e32 v236, v230, v238
	s_waitcnt lgkmcnt(0)
	v_mfma_f32_16x16x32_bf16 v[0:3], v[72:75], v[4:7], v[0:3]
	ds_read_b128 v[4:7], v220 offset:192
	v_fmac_f32_e32 v237, v230, v241
	s_waitcnt lgkmcnt(0)
	v_mfma_f32_16x16x32_bf16 v[0:3], v[68:71], v[4:7], v[0:3]
	v_mov_b64_e32 v[4:5], v[248:249]
	s_nop 1
	v_lshlrev_b32_e32 v6, 16, v4
	v_and_b32_e32 v4, 0xffff0000, v4
	s_nop 2
	v_fma_f32 v1, v65, v4, v1
	v_mul_f32_e32 v4, 0x3d372713, v1
	v_mul_f32_e32 v4, v1, v4
	v_fma_f32 v4, v1, v4, v1
	v_mul_f32_e32 v4, 0x3f4c422a, v4
	v_add_f32_e32 v4, v4, v4
	v_mul_f32_e32 v4, 0x3fb8aa3b, v4
	v_exp_f32_e32 v4, v4
	v_fma_f32 v0, v64, v6, v0
	v_mul_f32_e32 v6, 0x3d372713, v0
	v_mul_f32_e32 v6, v0, v6
	v_add_f32_e32 v4, 1.0, v4
	v_rcp_f32_e32 v4, v4
	v_fma_f32 v6, v0, v6, v0
	v_mul_f32_e32 v6, 0x3f4c422a, v6
	v_add_f32_e32 v6, v6, v6
	v_sub_f32_e32 v4, 1.0, v4
	v_mul_f32_e32 v1, v1, v4
	v_lshlrev_b32_e32 v4, 16, v5
	v_fma_f32 v2, v66, v4, v2
	v_mul_f32_e32 v4, 0x3d372713, v2
	v_mul_f32_e32 v4, v2, v4
	v_fma_f32 v4, v2, v4, v2
	v_mul_f32_e32 v4, 0x3f4c422a, v4
	v_add_f32_e32 v4, v4, v4
	v_mul_f32_e32 v4, 0x3fb8aa3b, v4
	v_exp_f32_e32 v4, v4
	v_mul_f32_e32 v6, 0x3fb8aa3b, v6
	v_exp_f32_e32 v6, v6
	v_add_f32_e32 v4, 1.0, v4
	v_rcp_f32_e32 v4, v4
	v_add_f32_e32 v6, 1.0, v6
	v_rcp_f32_e32 v6, v6
	v_sub_f32_e32 v4, 1.0, v4
	v_mul_f32_e32 v2, v2, v4
	v_and_b32_e32 v4, 0xffff0000, v5
	v_fmac_f32_e32 v3, v67, v4
	v_mul_f32_e32 v4, 0x3d372713, v3
	v_mul_f32_e32 v4, v3, v4
	v_fma_f32 v4, v3, v4, v3
	v_mul_f32_e32 v4, 0x3f4c422a, v4
	v_add_f32_e32 v4, v4, v4
	v_mul_f32_e32 v4, 0x3fb8aa3b, v4
	v_exp_f32_e32 v4, v4
	v_sub_f32_e32 v6, 1.0, v6
	v_mul_f32_e32 v0, v0, v6
	v_cvt_pk_bf16_f32 v0, v0, v1
	v_add_f32_e32 v4, 1.0, v4
	v_rcp_f32_e32 v4, v4
	s_nop 0
	v_sub_f32_e32 v4, 1.0, v4
	v_mul_f32_e32 v3, v3, v4
	v_cvt_pk_bf16_f32 v1, v2, v3
	ds_write_b64 v234, v[0:1]
	ds_read_b128 v[0:3], v220 offset:4352
	ds_read_b128 v[4:7], v220 offset:4416
	s_waitcnt lgkmcnt(1)
	v_mfma_f32_16x16x32_bf16 v[0:3], v[80:83], v[0:3], 0
	s_waitcnt lgkmcnt(0)
	v_mfma_f32_16x16x32_bf16 v[0:3], v[76:79], v[4:7], v[0:3]
	ds_read_b128 v[4:7], v220 offset:4480
	s_waitcnt lgkmcnt(0)
	v_mfma_f32_16x16x32_bf16 v[0:3], v[72:75], v[4:7], v[0:3]
	ds_read_b128 v[4:7], v220 offset:4544
	s_waitcnt lgkmcnt(0)
	v_mfma_f32_16x16x32_bf16 v[0:3], v[68:71], v[4:7], v[0:3]
	v_mov_b64_e32 v[4:5], v[250:251]
	s_nop 1
	v_lshlrev_b32_e32 v6, 16, v4
	v_and_b32_e32 v4, 0xffff0000, v4
	s_nop 2
	v_fma_f32 v1, v65, v4, v1
	v_mul_f32_e32 v4, 0x3d372713, v1
	v_mul_f32_e32 v4, v1, v4
	v_fma_f32 v4, v1, v4, v1
	v_mul_f32_e32 v4, 0x3f4c422a, v4
	v_add_f32_e32 v4, v4, v4
	v_mul_f32_e32 v4, 0x3fb8aa3b, v4
	v_exp_f32_e32 v4, v4
	v_fma_f32 v0, v64, v6, v0
	v_mul_f32_e32 v6, 0x3d372713, v0
	v_mul_f32_e32 v6, v0, v6
	v_add_f32_e32 v4, 1.0, v4
	v_rcp_f32_e32 v4, v4
	v_fma_f32 v6, v0, v6, v0
	v_mul_f32_e32 v6, 0x3f4c422a, v6
	v_add_f32_e32 v6, v6, v6
	v_sub_f32_e32 v4, 1.0, v4
	v_mul_f32_e32 v1, v1, v4
	v_lshlrev_b32_e32 v4, 16, v5
	v_fma_f32 v2, v66, v4, v2
	v_mul_f32_e32 v4, 0x3d372713, v2
	v_mul_f32_e32 v4, v2, v4
	v_fma_f32 v4, v2, v4, v2
	v_mul_f32_e32 v4, 0x3f4c422a, v4
	v_add_f32_e32 v4, v4, v4
	v_mul_f32_e32 v4, 0x3fb8aa3b, v4
	v_exp_f32_e32 v4, v4
	v_mul_f32_e32 v6, 0x3fb8aa3b, v6
	v_exp_f32_e32 v6, v6
	v_add_f32_e32 v4, 1.0, v4
	v_rcp_f32_e32 v4, v4
	v_add_f32_e32 v6, 1.0, v6
	v_rcp_f32_e32 v6, v6
	v_sub_f32_e32 v4, 1.0, v4
	v_mul_f32_e32 v2, v2, v4
	v_and_b32_e32 v4, 0xffff0000, v5
	v_fmac_f32_e32 v3, v67, v4
	v_mul_f32_e32 v4, 0x3d372713, v3
	v_mul_f32_e32 v4, v3, v4
	v_fma_f32 v4, v3, v4, v3
	v_mul_f32_e32 v4, 0x3f4c422a, v4
	v_add_f32_e32 v4, v4, v4
	v_mul_f32_e32 v4, 0x3fb8aa3b, v4
	v_exp_f32_e32 v4, v4
	v_sub_f32_e32 v6, 1.0, v6
	v_mul_f32_e32 v0, v0, v6
	v_cvt_pk_bf16_f32 v0, v0, v1
	v_add_f32_e32 v4, 1.0, v4
	v_rcp_f32_e32 v4, v4
	s_nop 0
	v_sub_f32_e32 v4, 1.0, v4
	v_mul_f32_e32 v3, v3, v4
	v_cvt_pk_bf16_f32 v1, v2, v3
	ds_write_b64 v234, v[0:1] offset:16640
	v_mfma_f32_32x32x16_bf16 v[32:47], v[244:247], v[92:95], 0
	v_mfma_f32_32x32x16_bf16 v[48:63], v[244:247], v[84:87], 0
	s_nop 10
	v_fma_f32 v85, 0, v115, v32
	v_fmac_f32_e32 v85, 0, v114
	v_mfma_f32_32x32x16_bf16 v[16:31], v[244:247], v[88:91], 0
	v_fmamk_f32 v84, v115, 0x80000000, v48
	v_fmac_f32_e32 v84, 0, v114
	v_fma_f32 v86, -v115, v85, v49
	v_fmac_f32_e32 v86, v114, v84
	v_fma_f32 v84, v115, v84, v33
	v_fmac_f32_e32 v84, v114, v85
	v_fma_f32 v85, -v115, v84, v50
	v_fmac_f32_e32 v85, v114, v86
	v_fma_f32 v86, v115, v86, v34
	v_fmac_f32_e32 v86, v114, v84
	v_fma_f32 v84, -v115, v86, v51
	v_fmac_f32_e32 v84, v114, v85
	v_fma_f32 v85, v115, v85, v35
	v_fmac_f32_e32 v85, v114, v86
	v_fma_f32 v86, -v115, v85, v52
	v_fmac_f32_e32 v86, v114, v84
	v_fma_f32 v84, v115, v84, v36
	v_fmac_f32_e32 v84, v114, v85
	v_fma_f32 v85, -v115, v84, v53
	v_fmac_f32_e32 v85, v114, v86
	v_fma_f32 v86, v115, v86, v37
	v_fmac_f32_e32 v86, v114, v84
	v_fma_f32 v84, -v115, v86, v54
	v_fmac_f32_e32 v84, v114, v85
	v_fma_f32 v85, v115, v85, v38
	v_fmac_f32_e32 v85, v114, v86
	v_fma_f32 v86, -v115, v85, v55
	v_fmac_f32_e32 v86, v114, v84
	v_fma_f32 v84, v115, v84, v39
	v_fmac_f32_e32 v84, v114, v85
	v_fma_f32 v85, -v115, v84, v56
	v_fmac_f32_e32 v85, v114, v86
	v_fma_f32 v86, v115, v86, v40
	v_fmac_f32_e32 v86, v114, v84
	v_fma_f32 v84, -v115, v86, v57
	v_fmac_f32_e32 v84, v114, v85
	v_fma_f32 v85, v115, v85, v41
	v_fmac_f32_e32 v85, v114, v86
	v_fma_f32 v86, -v115, v85, v58
	v_fmac_f32_e32 v86, v114, v84
	v_fma_f32 v84, v115, v84, v42
	v_fmac_f32_e32 v84, v114, v85
	v_fma_f32 v85, -v115, v84, v59
	v_fmac_f32_e32 v85, v114, v86
	v_fma_f32 v86, v115, v86, v43
	v_fmac_f32_e32 v86, v114, v84
	v_fma_f32 v84, -v115, v86, v60
	v_fmac_f32_e32 v84, v114, v85
	v_fma_f32 v85, v115, v85, v44
	v_fmac_f32_e32 v85, v114, v86
	v_fma_f32 v86, -v115, v85, v61
	v_fmac_f32_e32 v86, v114, v84
	v_fma_f32 v84, v115, v84, v45
	v_fmac_f32_e32 v84, v114, v85
	v_fma_f32 v85, -v115, v84, v62
	v_fmac_f32_e32 v85, v114, v86
	v_fma_f32 v86, v115, v86, v46
	v_fmac_f32_e32 v86, v114, v84
	v_fma_f32 v84, -v115, v86, v63
	v_fmac_f32_e32 v84, v114, v85
	v_fma_f32 v85, v115, v85, v47
	v_fmac_f32_e32 v85, v114, v86
	ds_bpermute_b32 v86, v149, v84
	ds_bpermute_b32 v87, v149, v85
	v_mfma_f32_32x32x16_bf16 v[0:15], v[244:247], v[96:99], 0
	s_waitcnt lgkmcnt(1)
	v_cndmask_b32_e64 v84, v86, v84, s[0:1]
	s_waitcnt lgkmcnt(0)
	v_cndmask_b32_e64 v85, v87, v85, s[0:1]
	v_fma_f32 v84, -v231, v237, v84
	v_fmac_f32_e32 v85, v231, v236
	v_fmac_f32_e32 v84, v230, v236
	v_fmac_f32_e32 v85, v230, v237
	v_cndmask_b32_e64 v84, v84, v236, s[0:1]
	v_cndmask_b32_e64 v85, v85, v237, s[0:1]
	v_fma_f32 v48, -v115, v85, v48
	v_fma_f32 v32, v115, v84, v32
	v_fmac_f32_e32 v48, v114, v84
	v_fmac_f32_e32 v32, v114, v85
	v_fma_f32 v49, -v115, v32, v49
	v_fma_f32 v33, v115, v48, v33
	v_cvt_pk_bf16_f32 v84, v48, v32
	ds_write_b32 v137, v84
	v_fmac_f32_e32 v49, v114, v48
	v_fmac_f32_e32 v33, v114, v32
	v_cvt_pk_bf16_f32 v32, v49, v33
	ds_write_b32 v137, v32 offset:272
	v_fma_f32 v32, -v115, v33, v50
	v_fma_f32 v34, v115, v49, v34
	v_fmac_f32_e32 v32, v114, v49
	v_fmac_f32_e32 v34, v114, v33
	v_cvt_pk_bf16_f32 v33, v32, v34
	ds_write_b32 v137, v33 offset:544
	v_fma_f32 v33, -v115, v34, v51
	v_fmac_f32_e32 v33, v114, v32
	v_fma_f32 v32, v115, v32, v35
	v_fmac_f32_e32 v32, v114, v34
	v_cvt_pk_bf16_f32 v34, v33, v32
	ds_write_b32 v137, v34 offset:816
	v_fma_f32 v34, -v115, v32, v52
	v_fmac_f32_e32 v34, v114, v33
	v_fma_f32 v33, v115, v33, v36
	v_fmac_f32_e32 v33, v114, v32
	v_cvt_pk_bf16_f32 v32, v34, v33
	ds_write_b32 v137, v32 offset:1088
	v_fma_f32 v32, -v115, v33, v53
	v_fmac_f32_e32 v32, v114, v34
	v_fma_f32 v34, v115, v34, v37
	v_fmac_f32_e32 v34, v114, v33
	v_cvt_pk_bf16_f32 v33, v32, v34
	ds_write_b32 v137, v33 offset:1360
	v_fma_f32 v33, -v115, v34, v54
	v_fmac_f32_e32 v33, v114, v32
	v_fma_f32 v32, v115, v32, v38
	v_fmac_f32_e32 v32, v114, v34
	v_cvt_pk_bf16_f32 v34, v33, v32
	ds_write_b32 v137, v34 offset:1632
	v_fma_f32 v34, -v115, v32, v55
	v_fmac_f32_e32 v34, v114, v33
	v_fma_f32 v33, v115, v33, v39
	v_fmac_f32_e32 v33, v114, v32
	v_cvt_pk_bf16_f32 v32, v34, v33
	ds_write_b32 v137, v32 offset:1904
	v_fma_f32 v32, -v115, v33, v56
	v_fmac_f32_e32 v32, v114, v34
	v_fma_f32 v34, v115, v34, v40
	v_fmac_f32_e32 v34, v114, v33
	v_cvt_pk_bf16_f32 v33, v32, v34
	ds_write_b32 v137, v33 offset:2176
	v_fma_f32 v33, -v115, v34, v57
	v_fmac_f32_e32 v33, v114, v32
	v_fma_f32 v32, v115, v32, v41
	v_fmac_f32_e32 v32, v114, v34
	v_cvt_pk_bf16_f32 v34, v33, v32
	ds_write_b32 v137, v34 offset:2448
	v_fma_f32 v34, -v115, v32, v58
	v_fmac_f32_e32 v34, v114, v33
	v_fma_f32 v33, v115, v33, v42
	v_fmac_f32_e32 v33, v114, v32
	v_cvt_pk_bf16_f32 v32, v34, v33
	ds_write_b32 v137, v32 offset:2720
	v_fma_f32 v32, -v115, v33, v59
	v_fmac_f32_e32 v32, v114, v34
	v_fma_f32 v34, v115, v34, v43
	v_fmac_f32_e32 v34, v114, v33
	v_cvt_pk_bf16_f32 v33, v32, v34
	ds_write_b32 v137, v33 offset:2992
	v_fma_f32 v33, -v115, v34, v60
	v_fmac_f32_e32 v33, v114, v32
	v_fma_f32 v32, v115, v32, v44
	v_fmac_f32_e32 v32, v114, v34
	v_cvt_pk_bf16_f32 v34, v33, v32
	ds_write_b32 v137, v34 offset:3264
	v_fma_f32 v34, -v115, v32, v61
	v_fmac_f32_e32 v34, v114, v33
	v_fma_f32 v33, v115, v33, v45
	v_fmac_f32_e32 v33, v114, v32
	v_cvt_pk_bf16_f32 v32, v34, v33
	ds_write_b32 v137, v32 offset:3536
	v_fma_f32 v32, -v115, v33, v62
	v_fmac_f32_e32 v32, v114, v34
	v_fma_f32 v34, v115, v34, v46
	v_fmac_f32_e32 v34, v114, v33
	v_cvt_pk_bf16_f32 v33, v32, v34
	ds_write_b32 v137, v33 offset:3808
	v_fma_f32 v33, -v115, v34, v63
	v_fmac_f32_e32 v33, v114, v32
	v_fmac_f32_e32 v47, v115, v32
	v_fmac_f32_e32 v47, v114, v34
	v_cvt_pk_bf16_f32 v32, v33, v47
	v_fma_f32 v33, 0, v113, v0
	ds_write_b32 v137, v32 offset:4080
	v_fmamk_f32 v32, v113, 0x80000000, v16
	v_fmac_f32_e32 v33, 0, v112
	v_fmac_f32_e32 v32, 0, v112
	v_fma_f32 v34, -v113, v33, v17
	v_fmac_f32_e32 v34, v112, v32
	v_fma_f32 v32, v113, v32, v1
	v_fmac_f32_e32 v32, v112, v33
	v_fma_f32 v33, -v113, v32, v18
	v_fmac_f32_e32 v33, v112, v34
	v_fma_f32 v34, v113, v34, v2
	v_fmac_f32_e32 v34, v112, v32
	v_fma_f32 v32, -v113, v34, v19
	v_fmac_f32_e32 v32, v112, v33
	v_fma_f32 v33, v113, v33, v3
	v_fmac_f32_e32 v33, v112, v34
	v_fma_f32 v34, -v113, v33, v20
	v_fmac_f32_e32 v34, v112, v32
	v_fma_f32 v32, v113, v32, v4
	v_fmac_f32_e32 v32, v112, v33
	v_fma_f32 v33, -v113, v32, v21
	v_fmac_f32_e32 v33, v112, v34
	v_fma_f32 v34, v113, v34, v5
	v_fmac_f32_e32 v34, v112, v32
	v_fma_f32 v32, -v113, v34, v22
	v_fmac_f32_e32 v32, v112, v33
	v_fma_f32 v33, v113, v33, v6
	v_fmac_f32_e32 v33, v112, v34
	v_fma_f32 v34, -v113, v33, v23
	v_fmac_f32_e32 v34, v112, v32
	v_fma_f32 v32, v113, v32, v7
	v_fmac_f32_e32 v32, v112, v33
	v_fma_f32 v33, -v113, v32, v24
	v_fmac_f32_e32 v33, v112, v34
	v_fma_f32 v34, v113, v34, v8
	v_fmac_f32_e32 v34, v112, v32
	v_fma_f32 v32, -v113, v34, v25
	v_fmac_f32_e32 v32, v112, v33
	v_fma_f32 v33, v113, v33, v9
	v_fmac_f32_e32 v33, v112, v34
	v_fma_f32 v34, -v113, v33, v26
	v_fmac_f32_e32 v34, v112, v32
	v_fma_f32 v32, v113, v32, v10
	v_fmac_f32_e32 v32, v112, v33
	v_fma_f32 v33, -v113, v32, v27
	v_fmac_f32_e32 v33, v112, v34
	v_fma_f32 v34, v113, v34, v11
	v_fmac_f32_e32 v34, v112, v32
	v_fma_f32 v32, -v113, v34, v28
	v_fmac_f32_e32 v32, v112, v33
	v_fma_f32 v33, v113, v33, v12
	v_fmac_f32_e32 v33, v112, v34
	v_fma_f32 v34, -v113, v33, v29
	v_fmac_f32_e32 v34, v112, v32
	v_fma_f32 v32, v113, v32, v13
	v_fmac_f32_e32 v32, v112, v33
	v_fma_f32 v33, -v113, v32, v30
	v_fmac_f32_e32 v33, v112, v34
	v_fma_f32 v34, v113, v34, v14
	v_fmac_f32_e32 v34, v112, v32
	v_fma_f32 v32, -v113, v34, v31
	v_fmac_f32_e32 v32, v112, v33
	v_fma_f32 v33, v113, v33, v15
	v_fmac_f32_e32 v33, v112, v34
	ds_bpermute_b32 v34, v149, v32
	ds_bpermute_b32 v35, v149, v33
	v_cndmask_b32_e64 v236, v226, v126, s[6:7]
	v_cndmask_b32_e64 v237, v227, v127, s[6:7]
	s_waitcnt lgkmcnt(1)
	v_cndmask_b32_e64 v32, v34, v32, s[0:1]
	s_waitcnt lgkmcnt(0)
	v_cndmask_b32_e64 v33, v35, v33, s[0:1]
	v_fma_f32 v32, -v229, v232, v32
	v_fmac_f32_e32 v33, v229, v233
	v_fmac_f32_e32 v32, v228, v233
	v_fmac_f32_e32 v33, v228, v232
	v_cndmask_b32_e64 v32, v32, v233, s[0:1]
	v_cndmask_b32_e64 v33, v33, v232, s[0:1]
	v_fma_f32 v16, -v113, v33, v16
	v_fma_f32 v0, v113, v32, v0
	v_fmac_f32_e32 v16, v112, v32
	v_fmac_f32_e32 v0, v112, v33
	v_fma_f32 v17, -v113, v0, v17
	v_fma_f32 v1, v113, v16, v1
	v_cvt_pk_bf16_f32 v32, v16, v0
	ds_write_b32 v137, v32 offset:128
	v_fmac_f32_e32 v17, v112, v16
	v_fmac_f32_e32 v1, v112, v0
	v_cvt_pk_bf16_f32 v0, v17, v1
	ds_write_b32 v137, v0 offset:400
	v_fma_f32 v0, -v113, v1, v18
	v_fma_f32 v2, v113, v17, v2
	v_fmac_f32_e32 v0, v112, v17
	v_fmac_f32_e32 v2, v112, v1
	v_cvt_pk_bf16_f32 v1, v0, v2
	ds_write_b32 v137, v1 offset:672
	v_fma_f32 v1, -v113, v2, v19
	v_fmac_f32_e32 v1, v112, v0
	v_fma_f32 v0, v113, v0, v3
	v_fmac_f32_e32 v0, v112, v2
	v_cvt_pk_bf16_f32 v2, v1, v0
	ds_write_b32 v137, v2 offset:944
	v_fma_f32 v2, -v113, v0, v20
	v_fmac_f32_e32 v2, v112, v1
	v_fma_f32 v1, v113, v1, v4
	v_fmac_f32_e32 v1, v112, v0
	v_cvt_pk_bf16_f32 v0, v2, v1
	ds_write_b32 v137, v0 offset:1216
	v_fma_f32 v0, -v113, v1, v21
	v_fmac_f32_e32 v0, v112, v2
	v_fma_f32 v2, v113, v2, v5
	v_fmac_f32_e32 v2, v112, v1
	v_cvt_pk_bf16_f32 v1, v0, v2
	ds_write_b32 v137, v1 offset:1488
	v_fma_f32 v1, -v113, v2, v22
	v_fmac_f32_e32 v1, v112, v0
	v_fma_f32 v0, v113, v0, v6
	v_fmac_f32_e32 v0, v112, v2
	v_cvt_pk_bf16_f32 v2, v1, v0
	ds_write_b32 v137, v2 offset:1760
	v_fma_f32 v2, -v113, v0, v23
	v_fmac_f32_e32 v2, v112, v1
	v_fma_f32 v1, v113, v1, v7
	v_fmac_f32_e32 v1, v112, v0
	v_cvt_pk_bf16_f32 v0, v2, v1
	ds_write_b32 v137, v0 offset:2032
	v_fma_f32 v0, -v113, v1, v24
	v_fmac_f32_e32 v0, v112, v2
	v_fma_f32 v2, v113, v2, v8
	v_fmac_f32_e32 v2, v112, v1
	v_cvt_pk_bf16_f32 v1, v0, v2
	ds_write_b32 v137, v1 offset:2304
	v_fma_f32 v1, -v113, v2, v25
	v_fmac_f32_e32 v1, v112, v0
	v_fma_f32 v0, v113, v0, v9
	v_fmac_f32_e32 v0, v112, v2
	v_cvt_pk_bf16_f32 v2, v1, v0
	ds_write_b32 v137, v2 offset:2576
	v_fma_f32 v2, -v113, v0, v26
	v_fmac_f32_e32 v2, v112, v1
	v_fma_f32 v1, v113, v1, v10
	v_fmac_f32_e32 v1, v112, v0
	v_cvt_pk_bf16_f32 v0, v2, v1
	ds_write_b32 v137, v0 offset:2848
	v_fma_f32 v0, -v113, v1, v27
	v_fmac_f32_e32 v0, v112, v2
	v_fma_f32 v2, v113, v2, v11
	v_fmac_f32_e32 v2, v112, v1
	v_cvt_pk_bf16_f32 v1, v0, v2
	ds_write_b32 v137, v1 offset:3120
	v_fma_f32 v1, -v113, v2, v28
	v_fmac_f32_e32 v1, v112, v0
	v_fma_f32 v0, v113, v0, v12
	v_fmac_f32_e32 v0, v112, v2
	v_cvt_pk_bf16_f32 v2, v1, v0
	ds_write_b32 v137, v2 offset:3392
	v_fma_f32 v2, -v113, v0, v29
	v_fmac_f32_e32 v2, v112, v1
	v_fma_f32 v1, v113, v1, v13
	v_fmac_f32_e32 v1, v112, v0
	v_cvt_pk_bf16_f32 v0, v2, v1
	ds_write_b32 v137, v0 offset:3664
	v_fma_f32 v0, -v113, v1, v30
	v_fmac_f32_e32 v0, v112, v2
	v_fma_f32 v2, v113, v2, v14
	v_fmac_f32_e32 v2, v112, v1
	v_cvt_pk_bf16_f32 v1, v0, v2
	ds_write_b32 v137, v1 offset:3936
	v_fma_f32 v1, -v113, v2, v31
	v_fmac_f32_e32 v15, v113, v0
	v_fmac_f32_e32 v1, v112, v0
	v_fmac_f32_e32 v15, v112, v2
	v_cvt_pk_bf16_f32 v0, v1, v15
	ds_write_b32 v137, v0 offset:4208
	ds_read_b128 v[0:3], v220
	ds_read_b128 v[4:7], v220 offset:64
	s_waitcnt lgkmcnt(1)
	v_mfma_f32_16x16x32_bf16 v[0:3], v[80:83], v[0:3], 0
	v_cndmask_b32_e64 v232, v224, v124, s[6:7]
	v_cndmask_b32_e64 v233, v225, v125, s[6:7]
	s_mov_b64 s[6:7], 0
	s_waitcnt lgkmcnt(0)
	v_mfma_f32_16x16x32_bf16 v[0:3], v[76:79], v[4:7], v[0:3]
	ds_read_b128 v[4:7], v220 offset:128
	s_waitcnt lgkmcnt(0)
	v_mfma_f32_16x16x32_bf16 v[0:3], v[72:75], v[4:7], v[0:3]
	ds_read_b128 v[4:7], v220 offset:192
	s_waitcnt lgkmcnt(0)
	v_mfma_f32_16x16x32_bf16 v[0:3], v[68:71], v[4:7], v[0:3]
	v_mov_b64_e32 v[4:5], v[252:253]
	s_nop 1
	v_lshlrev_b32_e32 v6, 16, v4
	v_and_b32_e32 v4, 0xffff0000, v4
	s_nop 2
	v_fma_f32 v1, v65, v4, v1
	v_mul_f32_e32 v4, 0x3d372713, v1
	v_mul_f32_e32 v4, v1, v4
	v_fma_f32 v4, v1, v4, v1
	v_mul_f32_e32 v4, 0x3f4c422a, v4
	v_add_f32_e32 v4, v4, v4
	v_mul_f32_e32 v4, 0x3fb8aa3b, v4
	v_exp_f32_e32 v4, v4
	v_fma_f32 v0, v64, v6, v0
	v_mul_f32_e32 v6, 0x3d372713, v0
	v_mul_f32_e32 v6, v0, v6
	v_add_f32_e32 v4, 1.0, v4
	v_rcp_f32_e32 v4, v4
	v_fma_f32 v6, v0, v6, v0
	v_mul_f32_e32 v6, 0x3f4c422a, v6
	v_add_f32_e32 v6, v6, v6
	v_sub_f32_e32 v4, 1.0, v4
	v_mul_f32_e32 v1, v1, v4
	v_lshlrev_b32_e32 v4, 16, v5
	v_fma_f32 v2, v66, v4, v2
	v_mul_f32_e32 v4, 0x3d372713, v2
	v_mul_f32_e32 v4, v2, v4
	v_fma_f32 v4, v2, v4, v2
	v_mul_f32_e32 v4, 0x3f4c422a, v4
	v_add_f32_e32 v4, v4, v4
	v_mul_f32_e32 v4, 0x3fb8aa3b, v4
	v_exp_f32_e32 v4, v4
	v_mul_f32_e32 v6, 0x3fb8aa3b, v6
	v_exp_f32_e32 v6, v6
	v_add_f32_e32 v4, 1.0, v4
	v_rcp_f32_e32 v4, v4
	v_add_f32_e32 v6, 1.0, v6
	v_rcp_f32_e32 v6, v6
	v_sub_f32_e32 v4, 1.0, v4
	v_mul_f32_e32 v2, v2, v4
	v_and_b32_e32 v4, 0xffff0000, v5
	v_fmac_f32_e32 v3, v67, v4
	v_mul_f32_e32 v4, 0x3d372713, v3
	v_mul_f32_e32 v4, v3, v4
	v_fma_f32 v4, v3, v4, v3
	v_mul_f32_e32 v4, 0x3f4c422a, v4
	v_add_f32_e32 v4, v4, v4
	v_mul_f32_e32 v4, 0x3fb8aa3b, v4
	v_exp_f32_e32 v4, v4
	v_sub_f32_e32 v6, 1.0, v6
	v_mul_f32_e32 v0, v0, v6
	v_cvt_pk_bf16_f32 v0, v0, v1
	v_add_f32_e32 v4, 1.0, v4
	v_rcp_f32_e32 v4, v4
	s_nop 0
	v_sub_f32_e32 v4, 1.0, v4
	v_mul_f32_e32 v3, v3, v4
	v_cvt_pk_bf16_f32 v1, v2, v3
	ds_write_b64 v234, v[0:1] offset:33280
	ds_read_b128 v[0:3], v220 offset:4352
	ds_read_b128 v[4:7], v220 offset:4416
	s_waitcnt lgkmcnt(1)
	v_mfma_f32_16x16x32_bf16 v[0:3], v[80:83], v[0:3], 0
	s_waitcnt lgkmcnt(0)
	v_mfma_f32_16x16x32_bf16 v[0:3], v[76:79], v[4:7], v[0:3]
	ds_read_b128 v[4:7], v220 offset:4480
	s_waitcnt lgkmcnt(0)
	v_mfma_f32_16x16x32_bf16 v[0:3], v[72:75], v[4:7], v[0:3]
	ds_read_b128 v[4:7], v220 offset:4544
	s_waitcnt lgkmcnt(0)
	v_mfma_f32_16x16x32_bf16 v[0:3], v[68:71], v[4:7], v[0:3]
	v_mov_b64_e32 v[4:5], v[242:243]
	s_nop 1
	v_lshlrev_b32_e32 v6, 16, v4
	v_and_b32_e32 v4, 0xffff0000, v4
	s_nop 2
	v_fma_f32 v1, v65, v4, v1
	v_mul_f32_e32 v4, 0x3d372713, v1
	v_mul_f32_e32 v4, v1, v4
	v_fma_f32 v4, v1, v4, v1
	v_mul_f32_e32 v4, 0x3f4c422a, v4
	v_add_f32_e32 v4, v4, v4
	v_mul_f32_e32 v4, 0x3fb8aa3b, v4
	v_exp_f32_e32 v4, v4
	v_fma_f32 v0, v64, v6, v0
	v_mul_f32_e32 v6, 0x3d372713, v0
	v_mul_f32_e32 v6, v0, v6
	v_add_f32_e32 v4, 1.0, v4
	v_rcp_f32_e32 v4, v4
	v_fma_f32 v6, v0, v6, v0
	v_mul_f32_e32 v6, 0x3f4c422a, v6
	v_add_f32_e32 v6, v6, v6
	v_sub_f32_e32 v4, 1.0, v4
	v_mul_f32_e32 v1, v1, v4
	v_lshlrev_b32_e32 v4, 16, v5
	v_fma_f32 v2, v66, v4, v2
	v_mul_f32_e32 v4, 0x3d372713, v2
	v_mul_f32_e32 v4, v2, v4
	v_fma_f32 v4, v2, v4, v2
	v_mul_f32_e32 v4, 0x3f4c422a, v4
	v_add_f32_e32 v4, v4, v4
	v_mul_f32_e32 v4, 0x3fb8aa3b, v4
	v_exp_f32_e32 v4, v4
	v_mul_f32_e32 v6, 0x3fb8aa3b, v6
	v_exp_f32_e32 v6, v6
	v_add_f32_e32 v4, 1.0, v4
	v_rcp_f32_e32 v4, v4
	v_add_f32_e32 v6, 1.0, v6
	v_rcp_f32_e32 v6, v6
	v_sub_f32_e32 v4, 1.0, v4
	v_mul_f32_e32 v2, v2, v4
	v_and_b32_e32 v4, 0xffff0000, v5
	v_fmac_f32_e32 v3, v67, v4
	v_mul_f32_e32 v4, 0x3d372713, v3
	v_mul_f32_e32 v4, v3, v4
	v_fma_f32 v4, v3, v4, v3
	v_mul_f32_e32 v4, 0x3f4c422a, v4
	v_add_f32_e32 v4, v4, v4
	v_mul_f32_e32 v4, 0x3fb8aa3b, v4
	v_exp_f32_e32 v4, v4
	v_sub_f32_e32 v6, 1.0, v6
	v_mul_f32_e32 v0, v0, v6
	v_cvt_pk_bf16_f32 v0, v0, v1
	v_add_f32_e32 v4, 1.0, v4
	v_rcp_f32_e32 v4, v4
	s_nop 0
	v_sub_f32_e32 v4, 1.0, v4
	v_mul_f32_e32 v3, v3, v4
	v_cvt_pk_bf16_f32 v1, v2, v3
	v_add_u32_e32 v2, v132, v155
	ds_write_b64 v2, v[0:1]
	v_lshl_or_b32 v0, s38, 7, v129
	v_ashrrev_i32_e32 v1, 31, v0
	v_lshl_add_u64 v[0:1], v[0:1], 2, s[16:17]
	global_load_dwordx2 v[112:113], v[0:1], off
	global_load_dwordx2 v[116:117], v[0:1], off offset:256
	s_waitcnt vmcnt(1)
	v_pk_mul_f32 v[2:3], v[112:113], v[112:113]
	s_nop 0
	v_sub_f32_e32 v2, v2, v3
	v_add_f32_e32 v3, v112, v112
	v_mul_f32_e32 v3, v113, v3
	v_mul_f32_e32 v4, v2, v2
	v_add_f32_e32 v2, v2, v2
	v_mul_f32_e32 v2, v3, v2
	v_fma_f32 v4, -v3, v3, v4
	v_mul_f32_e32 v3, v2, v2
	v_fma_f32 v3, v4, v4, -v3
	v_add_f32_e32 v4, v4, v4
	v_mul_f32_e32 v2, v2, v4
	v_mul_f32_e32 v4, v2, v2
	s_waitcnt vmcnt(0)
	v_pk_mul_f32 v[0:1], v[116:117], v[116:117]
	v_fma_f32 v228, v3, v3, -v4
	v_add_f32_e32 v3, v3, v3
	v_sub_f32_e32 v0, v0, v1
	v_add_f32_e32 v1, v116, v116
	v_mul_f32_e32 v229, v2, v3
	v_mul_f32_e32 v1, v117, v1
	v_mul_f32_e32 v2, v0, v0
	v_add_f32_e32 v0, v0, v0
	v_mul_f32_e32 v0, v1, v0
	v_fma_f32 v2, -v1, v1, v2
	v_mul_f32_e32 v1, v0, v0
	v_fma_f32 v1, v2, v2, -v1
	v_add_f32_e32 v2, v2, v2
	v_mul_f32_e32 v0, v0, v2
	v_mul_f32_e32 v2, v0, v0
	v_fma_f32 v230, v1, v1, -v2
	v_add_f32_e32 v1, v1, v1
	v_mul_f32_e32 v231, v0, v1
	v_lshl_add_u64 v[0:1], v[134:135], 0, s[10:11]
	s_or_b32 s10, s14, 1
	s_mov_b32 s11, s15
	s_lshl_b64 s[10:11], s[10:11], 10
	global_load_dwordx4 v[84:87], v[0:1], off
	v_lshl_add_u64 v[0:1], v[134:135], 0, s[10:11]
	s_or_b32 s10, s14, 2
	s_mov_b32 s11, s15
	s_lshl_b64 s[10:11], s[10:11], 10
	s_or_b32 s14, s14, 3
	global_load_dwordx4 v[88:91], v[0:1], off
	v_lshl_add_u64 v[0:1], v[134:135], 0, s[10:11]
	s_lshl_b64 s[10:11], s[14:15], 10
	s_lshl_b32 s14, s38, 4
	global_load_dwordx4 v[96:99], v[0:1], off
	v_lshl_add_u64 v[0:1], v[134:135], 0, s[10:11]
	v_or_b32_e32 v132, s14, v128
	global_load_dwordx4 v[92:95], v[0:1], off
	v_lshlrev_b64 v[0:1], 8, v[132:133]
	v_lshl_add_u64 v[0:1], v[138:139], 0, v[0:1]
	global_load_dwordx4 v[80:83], v[0:1], off
	global_load_dwordx4 v[76:79], v[0:1], off offset:64
	global_load_dwordx4 v[72:75], v[0:1], off offset:128
	global_load_dwordx4 v[68:71], v[0:1], off offset:192
	v_lshl_add_u64 v[0:1], s[14:15], 2, v[140:141]
	s_lshl_b32 s38, s38, 5
	global_load_dwordx4 v[64:67], v[0:1], off
	v_lshl_add_u64 v[118:119], v[144:145], 0, s[38:39]
	v_or_b32_e32 v0, s14, v151
	v_lshl_add_u32 v132, v0, 1, s3
	v_lshl_add_u64 v[0:1], v[118:119], 0, v[100:101]
	global_load_dwordx4 v[0:3], v[0:1], off
	v_lshl_add_u64 v[114:115], v[146:147], 0, s[38:39]
	v_lshl_add_u64 v[244:245], v[118:119], 0, v[106:107]
	v_lshl_add_u64 v[248:249], v[114:115], 0, v[102:103]
	v_lshl_add_u64 v[250:251], v[114:115], 0, v[104:105]
	v_lshl_add_u64 v[252:253], v[114:115], 0, v[108:109]
	v_lshl_add_u64 v[242:243], v[114:115], 0, v[110:111]
	global_load_dwordx4 v[244:247], v[244:245], off
	global_load_dwordx2 v[248:249], v[248:249], off
	global_load_dwordx2 v[250:251], v[250:251], off
	global_load_dwordx2 v[252:253], v[252:253], off
	global_load_dwordx2 v[242:243], v[242:243], off
	s_waitcnt vmcnt(0)
	v_mfma_f32_32x32x16_bf16 v[32:47], v[0:3], v[96:99], 0
	s_nop 11
	v_fma_f32 v235, 0, v113, v32
	v_mfma_f32_32x32x16_bf16 v[48:63], v[0:3], v[84:87], 0
	v_fmac_f32_e32 v235, 0, v112
	v_mfma_f32_32x32x16_bf16 v[16:31], v[0:3], v[88:91], 0
	s_nop 9
	v_fmamk_f32 v234, v113, 0x80000000, v48
	v_fmac_f32_e32 v234, 0, v112
	v_fma_f32 v238, -v113, v235, v49
	v_fmac_f32_e32 v238, v112, v234
	v_fma_f32 v234, v113, v234, v33
	v_fmac_f32_e32 v234, v112, v235
	v_fma_f32 v235, -v113, v234, v50
	v_fmac_f32_e32 v235, v112, v238
	v_fma_f32 v238, v113, v238, v34
	v_fmac_f32_e32 v238, v112, v234
	v_fma_f32 v234, -v113, v238, v51
	v_fmac_f32_e32 v234, v112, v235
	v_fma_f32 v235, v113, v235, v35
	v_fmac_f32_e32 v235, v112, v238
	v_fma_f32 v238, -v113, v235, v52
	v_fmac_f32_e32 v238, v112, v234
	v_fma_f32 v234, v113, v234, v36
	v_fmac_f32_e32 v234, v112, v235
	v_fma_f32 v235, -v113, v234, v53
	v_fmac_f32_e32 v235, v112, v238
	v_fma_f32 v238, v113, v238, v37
	v_fmac_f32_e32 v238, v112, v234
	v_fma_f32 v234, -v113, v238, v54
	v_fmac_f32_e32 v234, v112, v235
	v_fma_f32 v235, v113, v235, v38
	v_fmac_f32_e32 v235, v112, v238
	v_fma_f32 v238, -v113, v235, v55
	v_fmac_f32_e32 v238, v112, v234
	v_fma_f32 v234, v113, v234, v39
	v_fmac_f32_e32 v234, v112, v235
	v_fma_f32 v235, -v113, v234, v56
	v_fmac_f32_e32 v235, v112, v238
	v_fma_f32 v238, v113, v238, v40
	v_fmac_f32_e32 v238, v112, v234
	v_fma_f32 v234, -v113, v238, v57
	v_fmac_f32_e32 v234, v112, v235
	v_fma_f32 v235, v113, v235, v41
	v_fmac_f32_e32 v235, v112, v238
	v_fma_f32 v238, -v113, v235, v58
	v_fmac_f32_e32 v238, v112, v234
	v_fma_f32 v234, v113, v234, v42
	v_fmac_f32_e32 v234, v112, v235
	v_fma_f32 v235, -v113, v234, v59
	v_fmac_f32_e32 v235, v112, v238
	v_fma_f32 v238, v113, v238, v43
	v_fmac_f32_e32 v238, v112, v234
	v_fma_f32 v234, -v113, v238, v60
	v_fmac_f32_e32 v234, v112, v235
	v_fma_f32 v235, v113, v235, v44
	v_fmac_f32_e32 v235, v112, v238
	v_fma_f32 v238, -v113, v235, v61
	v_fmac_f32_e32 v238, v112, v234
	v_fma_f32 v234, v113, v234, v45
	v_fmac_f32_e32 v234, v112, v235
	v_fma_f32 v235, -v113, v234, v62
	v_fmac_f32_e32 v235, v112, v238
	v_fma_f32 v238, v113, v238, v46
	v_fmac_f32_e32 v238, v112, v234
	v_fma_f32 v234, -v113, v238, v63
	v_fmac_f32_e32 v234, v112, v235
	v_fma_f32 v235, v113, v235, v47
	v_fmac_f32_e32 v235, v112, v238
	ds_bpermute_b32 v238, v149, v234
	ds_bpermute_b32 v239, v149, v235
	v_mfma_f32_32x32x16_bf16 v[0:15], v[0:3], v[92:95], 0
	s_waitcnt lgkmcnt(1)
	v_cndmask_b32_e64 v240, v238, v234, s[0:1]
	s_waitcnt lgkmcnt(0)
	v_cndmask_b32_e64 v241, v239, v235, s[0:1]
	v_cndmask_b32_e64 v238, v234, v238, s[0:1]
	v_cndmask_b32_e64 v234, v235, v239, s[0:1]
	v_fma_f32 v239, -v229, v233, v240
	v_fmac_f32_e32 v241, v229, v232
	v_fmac_f32_e32 v239, v228, v232
	v_fmac_f32_e32 v241, v228, v233
	v_cndmask_b32_e64 v232, v239, v232, s[0:1]
	v_cndmask_b32_e64 v233, v241, v233, s[0:1]
	v_fma_f32 v48, -v113, v233, v48
	v_fma_f32 v32, v113, v232, v32
	v_fmac_f32_e32 v48, v112, v232
	v_fmac_f32_e32 v32, v112, v233
	v_fma_f32 v49, -v113, v32, v49
	v_fma_f32 v33, v113, v48, v33
	v_cvt_pk_bf16_f32 v232, v48, v32
	ds_write_b32 v137, v232
	v_fmac_f32_e32 v49, v112, v48
	v_fmac_f32_e32 v33, v112, v32
	v_cvt_pk_bf16_f32 v32, v49, v33
	ds_write_b32 v137, v32 offset:272
	v_fma_f32 v32, -v113, v33, v50
	v_fma_f32 v34, v113, v49, v34
	v_fmac_f32_e32 v32, v112, v49
	v_fmac_f32_e32 v34, v112, v33
	v_cvt_pk_bf16_f32 v33, v32, v34
	ds_write_b32 v137, v33 offset:544
	v_fma_f32 v33, -v113, v34, v51
	v_fmac_f32_e32 v33, v112, v32
	v_fma_f32 v32, v113, v32, v35
	v_fmac_f32_e32 v32, v112, v34
	v_cvt_pk_bf16_f32 v34, v33, v32
	ds_write_b32 v137, v34 offset:816
	v_fma_f32 v34, -v113, v32, v52
	v_fmac_f32_e32 v34, v112, v33
	v_fma_f32 v33, v113, v33, v36
	v_fmac_f32_e32 v33, v112, v32
	v_cvt_pk_bf16_f32 v32, v34, v33
	ds_write_b32 v137, v32 offset:1088
	v_fma_f32 v32, -v113, v33, v53
	v_fmac_f32_e32 v32, v112, v34
	v_fma_f32 v34, v113, v34, v37
	v_fmac_f32_e32 v34, v112, v33
	v_cvt_pk_bf16_f32 v33, v32, v34
	ds_write_b32 v137, v33 offset:1360
	v_fma_f32 v33, -v113, v34, v54
	v_fmac_f32_e32 v33, v112, v32
	v_fma_f32 v32, v113, v32, v38
	v_fmac_f32_e32 v32, v112, v34
	v_cvt_pk_bf16_f32 v34, v33, v32
	ds_write_b32 v137, v34 offset:1632
	v_fma_f32 v34, -v113, v32, v55
	v_fmac_f32_e32 v34, v112, v33
	v_fma_f32 v33, v113, v33, v39
	v_fmac_f32_e32 v33, v112, v32
	v_cvt_pk_bf16_f32 v32, v34, v33
	ds_write_b32 v137, v32 offset:1904
	v_fma_f32 v32, -v113, v33, v56
	v_fmac_f32_e32 v32, v112, v34
	v_fma_f32 v34, v113, v34, v40
	v_fmac_f32_e32 v34, v112, v33
	v_cvt_pk_bf16_f32 v33, v32, v34
	ds_write_b32 v137, v33 offset:2176
	v_fma_f32 v33, -v113, v34, v57
	v_fmac_f32_e32 v33, v112, v32
	v_fma_f32 v32, v113, v32, v41
	v_fmac_f32_e32 v32, v112, v34
	v_cvt_pk_bf16_f32 v34, v33, v32
	ds_write_b32 v137, v34 offset:2448
	v_fma_f32 v34, -v113, v32, v58
	v_fmac_f32_e32 v34, v112, v33
	v_fma_f32 v33, v113, v33, v42
	v_fmac_f32_e32 v33, v112, v32
	v_cvt_pk_bf16_f32 v32, v34, v33
	ds_write_b32 v137, v32 offset:2720
	v_fma_f32 v32, -v113, v33, v59
	v_fmac_f32_e32 v32, v112, v34
	v_fma_f32 v34, v113, v34, v43
	v_fmac_f32_e32 v34, v112, v33
	v_cvt_pk_bf16_f32 v33, v32, v34
	ds_write_b32 v137, v33 offset:2992
	v_fma_f32 v33, -v113, v34, v60
	v_fmac_f32_e32 v33, v112, v32
	v_fma_f32 v32, v113, v32, v44
	v_fmac_f32_e32 v32, v112, v34
	v_cvt_pk_bf16_f32 v34, v33, v32
	ds_write_b32 v137, v34 offset:3264
	v_fma_f32 v34, -v113, v32, v61
	v_fmac_f32_e32 v34, v112, v33
	v_fma_f32 v33, v113, v33, v45
	v_fmac_f32_e32 v33, v112, v32
	v_cvt_pk_bf16_f32 v32, v34, v33
	ds_write_b32 v137, v32 offset:3536
	v_fma_f32 v32, -v113, v33, v62
	v_fmac_f32_e32 v32, v112, v34
	v_fma_f32 v34, v113, v34, v46
	v_fmac_f32_e32 v34, v112, v33
	v_cvt_pk_bf16_f32 v33, v32, v34
	ds_write_b32 v137, v33 offset:3808
	v_fma_f32 v33, -v113, v34, v63
	v_fmac_f32_e32 v33, v112, v32
	v_fmac_f32_e32 v47, v113, v32
	v_fmac_f32_e32 v47, v112, v34
	v_cvt_pk_bf16_f32 v32, v33, v47
	v_fma_f32 v33, 0, v117, v0
	ds_write_b32 v137, v32 offset:4080
	v_fmamk_f32 v32, v117, 0x80000000, v16
	v_fmac_f32_e32 v33, 0, v116
	v_fmac_f32_e32 v32, 0, v116
	v_fma_f32 v34, -v117, v33, v17
	v_fmac_f32_e32 v34, v116, v32
	v_fma_f32 v32, v117, v32, v1
	v_fmac_f32_e32 v32, v116, v33
	v_fma_f32 v33, -v117, v32, v18
	v_fmac_f32_e32 v33, v116, v34
	v_fma_f32 v34, v117, v34, v2
	v_fmac_f32_e32 v34, v116, v32
	v_fma_f32 v32, -v117, v34, v19
	v_fmac_f32_e32 v32, v116, v33
	v_fma_f32 v33, v117, v33, v3
	v_fmac_f32_e32 v33, v116, v34
	v_fma_f32 v34, -v117, v33, v20
	v_fmac_f32_e32 v34, v116, v32
	v_fma_f32 v32, v117, v32, v4
	v_fmac_f32_e32 v32, v116, v33
	v_fma_f32 v33, -v117, v32, v21
	v_fmac_f32_e32 v33, v116, v34
	v_fma_f32 v34, v117, v34, v5
	v_fmac_f32_e32 v34, v116, v32
	v_fma_f32 v32, -v117, v34, v22
	v_fmac_f32_e32 v32, v116, v33
	v_fma_f32 v33, v117, v33, v6
	v_fmac_f32_e32 v33, v116, v34
	v_fma_f32 v34, -v117, v33, v23
	v_fmac_f32_e32 v34, v116, v32
	v_fma_f32 v32, v117, v32, v7
	v_fmac_f32_e32 v32, v116, v33
	v_fma_f32 v33, -v117, v32, v24
	v_fmac_f32_e32 v33, v116, v34
	v_fma_f32 v34, v117, v34, v8
	v_fmac_f32_e32 v34, v116, v32
	v_fma_f32 v32, -v117, v34, v25
	v_fmac_f32_e32 v32, v116, v33
	v_fma_f32 v33, v117, v33, v9
	v_fmac_f32_e32 v33, v116, v34
	v_fma_f32 v34, -v117, v33, v26
	v_fmac_f32_e32 v34, v116, v32
	v_fma_f32 v32, v117, v32, v10
	v_fmac_f32_e32 v32, v116, v33
	v_fma_f32 v33, -v117, v32, v27
	v_fmac_f32_e32 v33, v116, v34
	v_fma_f32 v34, v117, v34, v11
	v_fmac_f32_e32 v34, v116, v32
	v_fma_f32 v32, -v117, v34, v28
	v_fmac_f32_e32 v32, v116, v33
	v_fma_f32 v33, v117, v33, v12
	v_fmac_f32_e32 v33, v116, v34
	v_fma_f32 v34, -v117, v33, v29
	v_fmac_f32_e32 v34, v116, v32
	v_fma_f32 v32, v117, v32, v13
	v_fmac_f32_e32 v32, v116, v33
	v_fma_f32 v33, -v117, v32, v30
	v_fmac_f32_e32 v33, v116, v34
	v_fma_f32 v34, v117, v34, v14
	v_fmac_f32_e32 v34, v116, v32
	v_fma_f32 v32, -v117, v34, v31
	v_fmac_f32_e32 v32, v116, v33
	v_fma_f32 v33, v117, v33, v15
	v_fmac_f32_e32 v33, v116, v34
	ds_bpermute_b32 v34, v149, v32
	ds_bpermute_b32 v35, v149, v33
	v_fmac_f32_e32 v234, v229, v239
	v_fma_f32 v235, -v229, v241, v238
	v_fmac_f32_e32 v234, v228, v241
	s_waitcnt lgkmcnt(1)
	v_cndmask_b32_e64 v36, v34, v32, s[0:1]
	s_waitcnt lgkmcnt(0)
	v_cndmask_b32_e64 v37, v35, v33, s[0:1]
	v_cndmask_b32_e64 v232, v33, v35, s[0:1]
	v_fma_f32 v33, -v231, v237, v36
	v_fmac_f32_e32 v37, v231, v236
	v_fmac_f32_e32 v33, v230, v236
	v_fmac_f32_e32 v37, v230, v237
	v_cndmask_b32_e64 v32, v32, v34, s[0:1]
	v_cndmask_b32_e64 v34, v33, v236, s[0:1]
	v_cndmask_b32_e64 v35, v37, v237, s[0:1]
	v_fma_f32 v16, -v117, v35, v16
	v_fma_f32 v0, v117, v34, v0
	v_fmac_f32_e32 v16, v116, v34
	v_fmac_f32_e32 v0, v116, v35
	v_fma_f32 v17, -v117, v0, v17
	v_fma_f32 v1, v117, v16, v1
	v_fma_f32 v233, -v231, v37, v32
	v_cvt_pk_bf16_f32 v32, v16, v0
	ds_write_b32 v137, v32 offset:128
	v_fmac_f32_e32 v17, v116, v16
	v_fmac_f32_e32 v1, v116, v0
	v_cvt_pk_bf16_f32 v0, v17, v1
	ds_write_b32 v137, v0 offset:400
	v_fma_f32 v0, -v117, v1, v18
	v_fma_f32 v2, v117, v17, v2
	v_fmac_f32_e32 v0, v116, v17
	v_fmac_f32_e32 v2, v116, v1
	v_cvt_pk_bf16_f32 v1, v0, v2
	ds_write_b32 v137, v1 offset:672
	v_fma_f32 v1, -v117, v2, v19
	v_fmac_f32_e32 v1, v116, v0
	v_fma_f32 v0, v117, v0, v3
	v_fmac_f32_e32 v0, v116, v2
	v_cvt_pk_bf16_f32 v2, v1, v0
	ds_write_b32 v137, v2 offset:944
	v_fma_f32 v2, -v117, v0, v20
	v_fmac_f32_e32 v2, v116, v1
	v_fma_f32 v1, v117, v1, v4
	v_fmac_f32_e32 v1, v116, v0
	v_cvt_pk_bf16_f32 v0, v2, v1
	ds_write_b32 v137, v0 offset:1216
	v_fma_f32 v0, -v117, v1, v21
	v_fmac_f32_e32 v0, v116, v2
	v_fma_f32 v2, v117, v2, v5
	v_fmac_f32_e32 v2, v116, v1
	v_cvt_pk_bf16_f32 v1, v0, v2
	ds_write_b32 v137, v1 offset:1488
	v_fma_f32 v1, -v117, v2, v22
	v_fmac_f32_e32 v1, v116, v0
	v_fma_f32 v0, v117, v0, v6
	v_fmac_f32_e32 v0, v116, v2
	v_cvt_pk_bf16_f32 v2, v1, v0
	ds_write_b32 v137, v2 offset:1760
	v_fma_f32 v2, -v117, v0, v23
	v_fmac_f32_e32 v2, v116, v1
	v_fma_f32 v1, v117, v1, v7
	v_fmac_f32_e32 v1, v116, v0
	v_cvt_pk_bf16_f32 v0, v2, v1
	ds_write_b32 v137, v0 offset:2032
	v_fma_f32 v0, -v117, v1, v24
	v_fmac_f32_e32 v0, v116, v2
	v_fma_f32 v2, v117, v2, v8
	v_fmac_f32_e32 v2, v116, v1
	v_cvt_pk_bf16_f32 v1, v0, v2
	ds_write_b32 v137, v1 offset:2304
	v_fma_f32 v1, -v117, v2, v25
	v_fmac_f32_e32 v1, v116, v0
	v_fma_f32 v0, v117, v0, v9
	v_fmac_f32_e32 v0, v116, v2
	v_cvt_pk_bf16_f32 v2, v1, v0
	ds_write_b32 v137, v2 offset:2576
	v_fma_f32 v2, -v117, v0, v26
	v_fmac_f32_e32 v2, v116, v1
	v_fma_f32 v1, v117, v1, v10
	v_fmac_f32_e32 v1, v116, v0
	v_cvt_pk_bf16_f32 v0, v2, v1
	ds_write_b32 v137, v0 offset:2848
	v_fma_f32 v0, -v117, v1, v27
	v_fmac_f32_e32 v0, v116, v2
	v_fma_f32 v2, v117, v2, v11
	v_fmac_f32_e32 v2, v116, v1
	v_cvt_pk_bf16_f32 v1, v0, v2
	ds_write_b32 v137, v1 offset:3120
	v_fma_f32 v1, -v117, v2, v28
	v_fmac_f32_e32 v1, v116, v0
	v_fma_f32 v0, v117, v0, v12
	v_fmac_f32_e32 v0, v116, v2
	v_cvt_pk_bf16_f32 v2, v1, v0
	ds_write_b32 v137, v2 offset:3392
	v_fma_f32 v2, -v117, v0, v29
	v_fmac_f32_e32 v2, v116, v1
	v_fma_f32 v1, v117, v1, v13
	v_fmac_f32_e32 v1, v116, v0
	v_cvt_pk_bf16_f32 v0, v2, v1
	ds_write_b32 v137, v0 offset:3664
	v_fma_f32 v0, -v117, v1, v30
	v_fmac_f32_e32 v0, v116, v2
	v_fma_f32 v2, v117, v2, v14
	v_fmac_f32_e32 v2, v116, v1
	v_cvt_pk_bf16_f32 v1, v0, v2
	ds_write_b32 v137, v1 offset:3936
	v_fma_f32 v1, -v117, v2, v31
	v_fmac_f32_e32 v15, v117, v0
	v_fmac_f32_e32 v1, v116, v0
	v_fmac_f32_e32 v15, v116, v2
	v_cvt_pk_bf16_f32 v0, v1, v15
	ds_write_b32 v137, v0 offset:4208
	ds_read_b128 v[0:3], v220
	ds_read_b128 v[4:7], v220 offset:64
	s_waitcnt lgkmcnt(1)
	v_mfma_f32_16x16x32_bf16 v[0:3], v[80:83], v[0:3], 0
	v_add_u32_e32 v236, v132, v153
	v_fmac_f32_e32 v232, v231, v33
	v_fmac_f32_e32 v233, v230, v33
	s_waitcnt lgkmcnt(0)
	v_mfma_f32_16x16x32_bf16 v[0:3], v[76:79], v[4:7], v[0:3]
	ds_read_b128 v[4:7], v220 offset:128
	v_fmac_f32_e32 v232, v230, v37
	v_fmac_f32_e32 v235, v228, v239
	s_waitcnt lgkmcnt(0)
	v_mfma_f32_16x16x32_bf16 v[0:3], v[72:75], v[4:7], v[0:3]
	ds_read_b128 v[4:7], v220 offset:192
	s_waitcnt lgkmcnt(0)
	v_mfma_f32_16x16x32_bf16 v[0:3], v[68:71], v[4:7], v[0:3]
	v_mov_b64_e32 v[4:5], v[248:249]
	s_nop 1
	v_lshlrev_b32_e32 v6, 16, v4
	v_and_b32_e32 v4, 0xffff0000, v4
	s_nop 2
	v_fma_f32 v1, v65, v4, v1
	v_mul_f32_e32 v4, 0x3d372713, v1
	v_mul_f32_e32 v4, v1, v4
	v_fma_f32 v4, v1, v4, v1
	v_mul_f32_e32 v4, 0x3f4c422a, v4
	v_add_f32_e32 v4, v4, v4
	v_mul_f32_e32 v4, 0x3fb8aa3b, v4
	v_exp_f32_e32 v4, v4
	v_fma_f32 v0, v64, v6, v0
	v_mul_f32_e32 v6, 0x3d372713, v0
	v_mul_f32_e32 v6, v0, v6
	v_add_f32_e32 v4, 1.0, v4
	v_rcp_f32_e32 v4, v4
	v_fma_f32 v6, v0, v6, v0
	v_mul_f32_e32 v6, 0x3f4c422a, v6
	v_add_f32_e32 v6, v6, v6
	v_sub_f32_e32 v4, 1.0, v4
	v_mul_f32_e32 v1, v1, v4
	v_lshlrev_b32_e32 v4, 16, v5
	v_fma_f32 v2, v66, v4, v2
	v_mul_f32_e32 v4, 0x3d372713, v2
	v_mul_f32_e32 v4, v2, v4
	v_fma_f32 v4, v2, v4, v2
	v_mul_f32_e32 v4, 0x3f4c422a, v4
	v_add_f32_e32 v4, v4, v4
	v_mul_f32_e32 v4, 0x3fb8aa3b, v4
	v_exp_f32_e32 v4, v4
	v_mul_f32_e32 v6, 0x3fb8aa3b, v6
	v_exp_f32_e32 v6, v6
	v_add_f32_e32 v4, 1.0, v4
	v_rcp_f32_e32 v4, v4
	v_add_f32_e32 v6, 1.0, v6
	v_rcp_f32_e32 v6, v6
	v_sub_f32_e32 v4, 1.0, v4
	v_mul_f32_e32 v2, v2, v4
	v_and_b32_e32 v4, 0xffff0000, v5
	v_fmac_f32_e32 v3, v67, v4
	v_mul_f32_e32 v4, 0x3d372713, v3
	v_mul_f32_e32 v4, v3, v4
	v_fma_f32 v4, v3, v4, v3
	v_mul_f32_e32 v4, 0x3f4c422a, v4
	v_add_f32_e32 v4, v4, v4
	v_mul_f32_e32 v4, 0x3fb8aa3b, v4
	v_exp_f32_e32 v4, v4
	v_sub_f32_e32 v6, 1.0, v6
	v_mul_f32_e32 v0, v0, v6
	v_cvt_pk_bf16_f32 v0, v0, v1
	v_add_f32_e32 v4, 1.0, v4
	v_rcp_f32_e32 v4, v4
	s_nop 0
	v_sub_f32_e32 v4, 1.0, v4
	v_mul_f32_e32 v3, v3, v4
	v_cvt_pk_bf16_f32 v1, v2, v3
	ds_write_b64 v236, v[0:1]
	ds_read_b128 v[0:3], v220 offset:4352
	ds_read_b128 v[4:7], v220 offset:4416
	s_waitcnt lgkmcnt(1)
	v_mfma_f32_16x16x32_bf16 v[0:3], v[80:83], v[0:3], 0
	s_waitcnt lgkmcnt(0)
	v_mfma_f32_16x16x32_bf16 v[0:3], v[76:79], v[4:7], v[0:3]
	ds_read_b128 v[4:7], v220 offset:4480
	s_waitcnt lgkmcnt(0)
	v_mfma_f32_16x16x32_bf16 v[0:3], v[72:75], v[4:7], v[0:3]
	ds_read_b128 v[4:7], v220 offset:4544
	s_waitcnt lgkmcnt(0)
	v_mfma_f32_16x16x32_bf16 v[0:3], v[68:71], v[4:7], v[0:3]
	v_mov_b64_e32 v[4:5], v[250:251]
	s_nop 1
	v_lshlrev_b32_e32 v6, 16, v4
	v_and_b32_e32 v4, 0xffff0000, v4
	s_nop 2
	v_fma_f32 v1, v65, v4, v1
	v_mul_f32_e32 v4, 0x3d372713, v1
	v_mul_f32_e32 v4, v1, v4
	v_fma_f32 v4, v1, v4, v1
	v_mul_f32_e32 v4, 0x3f4c422a, v4
	v_add_f32_e32 v4, v4, v4
	v_mul_f32_e32 v4, 0x3fb8aa3b, v4
	v_exp_f32_e32 v4, v4
	v_fma_f32 v0, v64, v6, v0
	v_mul_f32_e32 v6, 0x3d372713, v0
	v_mul_f32_e32 v6, v0, v6
	v_add_f32_e32 v4, 1.0, v4
	v_rcp_f32_e32 v4, v4
	v_fma_f32 v6, v0, v6, v0
	v_mul_f32_e32 v6, 0x3f4c422a, v6
	v_add_f32_e32 v6, v6, v6
	v_sub_f32_e32 v4, 1.0, v4
	v_mul_f32_e32 v1, v1, v4
	v_lshlrev_b32_e32 v4, 16, v5
	v_fma_f32 v2, v66, v4, v2
	v_mul_f32_e32 v4, 0x3d372713, v2
	v_mul_f32_e32 v4, v2, v4
	v_fma_f32 v4, v2, v4, v2
	v_mul_f32_e32 v4, 0x3f4c422a, v4
	v_add_f32_e32 v4, v4, v4
	v_mul_f32_e32 v4, 0x3fb8aa3b, v4
	v_exp_f32_e32 v4, v4
	v_mul_f32_e32 v6, 0x3fb8aa3b, v6
	v_exp_f32_e32 v6, v6
	v_add_f32_e32 v4, 1.0, v4
	v_rcp_f32_e32 v4, v4
	v_add_f32_e32 v6, 1.0, v6
	v_rcp_f32_e32 v6, v6
	v_sub_f32_e32 v4, 1.0, v4
	v_mul_f32_e32 v2, v2, v4
	v_and_b32_e32 v4, 0xffff0000, v5
	v_fmac_f32_e32 v3, v67, v4
	v_mul_f32_e32 v4, 0x3d372713, v3
	v_mul_f32_e32 v4, v3, v4
	v_fma_f32 v4, v3, v4, v3
	v_mul_f32_e32 v4, 0x3f4c422a, v4
	v_add_f32_e32 v4, v4, v4
	v_mul_f32_e32 v4, 0x3fb8aa3b, v4
	v_exp_f32_e32 v4, v4
	v_sub_f32_e32 v6, 1.0, v6
	v_mul_f32_e32 v0, v0, v6
	v_cvt_pk_bf16_f32 v0, v0, v1
	v_add_f32_e32 v4, 1.0, v4
	v_rcp_f32_e32 v4, v4
	s_nop 0
	v_sub_f32_e32 v4, 1.0, v4
	v_mul_f32_e32 v3, v3, v4
	v_cvt_pk_bf16_f32 v1, v2, v3
	ds_write_b64 v236, v[0:1] offset:16640
	v_mfma_f32_32x32x16_bf16 v[48:63], v[244:247], v[96:99], 0
	v_mfma_f32_32x32x16_bf16 v[32:47], v[244:247], v[84:87], 0
	s_nop 10
	v_fma_f32 v85, 0, v113, v48
	v_fmac_f32_e32 v85, 0, v112
	v_mfma_f32_32x32x16_bf16 v[16:31], v[244:247], v[88:91], 0
	v_fmamk_f32 v84, v113, 0x80000000, v32
	v_fmac_f32_e32 v84, 0, v112
	v_fma_f32 v86, -v113, v85, v33
	v_fmac_f32_e32 v86, v112, v84
	v_fma_f32 v84, v113, v84, v49
	v_fmac_f32_e32 v84, v112, v85
	v_fma_f32 v85, -v113, v84, v34
	v_fmac_f32_e32 v85, v112, v86
	v_fma_f32 v86, v113, v86, v50
	v_fmac_f32_e32 v86, v112, v84
	v_fma_f32 v84, -v113, v86, v35
	v_fmac_f32_e32 v84, v112, v85
	v_fma_f32 v85, v113, v85, v51
	v_fmac_f32_e32 v85, v112, v86
	v_fma_f32 v86, -v113, v85, v36
	v_fmac_f32_e32 v86, v112, v84
	v_fma_f32 v84, v113, v84, v52
	v_fmac_f32_e32 v84, v112, v85
	v_fma_f32 v85, -v113, v84, v37
	v_fmac_f32_e32 v85, v112, v86
	v_fma_f32 v86, v113, v86, v53
	v_fmac_f32_e32 v86, v112, v84
	v_fma_f32 v84, -v113, v86, v38
	v_fmac_f32_e32 v84, v112, v85
	v_fma_f32 v85, v113, v85, v54
	v_fmac_f32_e32 v85, v112, v86
	v_fma_f32 v86, -v113, v85, v39
	v_fmac_f32_e32 v86, v112, v84
	v_fma_f32 v84, v113, v84, v55
	v_fmac_f32_e32 v84, v112, v85
	v_fma_f32 v85, -v113, v84, v40
	v_fmac_f32_e32 v85, v112, v86
	v_fma_f32 v86, v113, v86, v56
	v_fmac_f32_e32 v86, v112, v84
	v_fma_f32 v84, -v113, v86, v41
	v_fmac_f32_e32 v84, v112, v85
	v_fma_f32 v85, v113, v85, v57
	v_fmac_f32_e32 v85, v112, v86
	v_fma_f32 v86, -v113, v85, v42
	v_fmac_f32_e32 v86, v112, v84
	v_fma_f32 v84, v113, v84, v58
	v_fmac_f32_e32 v84, v112, v85
	v_fma_f32 v85, -v113, v84, v43
	v_fmac_f32_e32 v85, v112, v86
	v_fma_f32 v86, v113, v86, v59
	v_fmac_f32_e32 v86, v112, v84
	v_fma_f32 v84, -v113, v86, v44
	v_fmac_f32_e32 v84, v112, v85
	v_fma_f32 v85, v113, v85, v60
	v_fmac_f32_e32 v85, v112, v86
	v_fma_f32 v86, -v113, v85, v45
	v_fmac_f32_e32 v86, v112, v84
	v_fma_f32 v84, v113, v84, v61
	v_fmac_f32_e32 v84, v112, v85
	v_fma_f32 v85, -v113, v84, v46
	v_fmac_f32_e32 v85, v112, v86
	v_fma_f32 v86, v113, v86, v62
	v_fmac_f32_e32 v86, v112, v84
	v_fma_f32 v84, -v113, v86, v47
	v_fmac_f32_e32 v84, v112, v85
	v_fma_f32 v85, v113, v85, v63
	v_fmac_f32_e32 v85, v112, v86
	ds_bpermute_b32 v86, v149, v84
	ds_bpermute_b32 v87, v149, v85
	v_mfma_f32_32x32x16_bf16 v[0:15], v[244:247], v[92:95], 0
	s_waitcnt lgkmcnt(1)
	v_cndmask_b32_e64 v84, v86, v84, s[0:1]
	s_waitcnt lgkmcnt(0)
	v_cndmask_b32_e64 v85, v87, v85, s[0:1]
	v_fma_f32 v84, -v229, v234, v84
	v_fmac_f32_e32 v84, v228, v235
	v_fmac_f32_e32 v85, v229, v235
	v_fmac_f32_e32 v85, v228, v234
	v_cndmask_b32_e64 v84, v84, v235, s[0:1]
	v_cndmask_b32_e64 v85, v85, v234, s[0:1]
	v_fma_f32 v48, v113, v84, v48
	v_fma_f32 v32, -v113, v85, v32
	v_fmac_f32_e32 v48, v112, v85
	v_fmac_f32_e32 v32, v112, v84
	v_fma_f32 v33, -v113, v48, v33
	v_cvt_pk_bf16_f32 v84, v32, v48
	v_fmac_f32_e32 v33, v112, v32
	v_fma_f32 v32, v113, v32, v49
	v_fmac_f32_e32 v32, v112, v48
	v_fma_f32 v34, -v113, v32, v34
	ds_write_b32 v137, v84
	v_cvt_pk_bf16_f32 v48, v33, v32
	v_fmac_f32_e32 v34, v112, v33
	v_fma_f32 v33, v113, v33, v50
	ds_write_b32 v137, v48 offset:272
	v_fmac_f32_e32 v33, v112, v32
	v_cvt_pk_bf16_f32 v32, v34, v33
	ds_write_b32 v137, v32 offset:544
	v_fma_f32 v32, -v113, v33, v35
	v_fmac_f32_e32 v32, v112, v34
	v_fma_f32 v34, v113, v34, v51
	v_fmac_f32_e32 v34, v112, v33
	v_cvt_pk_bf16_f32 v33, v32, v34
	ds_write_b32 v137, v33 offset:816
	v_fma_f32 v33, -v113, v34, v36
	v_fmac_f32_e32 v33, v112, v32
	v_fma_f32 v32, v113, v32, v52
	v_fmac_f32_e32 v32, v112, v34
	v_cvt_pk_bf16_f32 v34, v33, v32
	ds_write_b32 v137, v34 offset:1088
	v_fma_f32 v34, -v113, v32, v37
	v_fmac_f32_e32 v34, v112, v33
	v_fma_f32 v33, v113, v33, v53
	v_fmac_f32_e32 v33, v112, v32
	v_cvt_pk_bf16_f32 v32, v34, v33
	ds_write_b32 v137, v32 offset:1360
	v_fma_f32 v32, -v113, v33, v38
	v_fmac_f32_e32 v32, v112, v34
	v_fma_f32 v34, v113, v34, v54
	v_fmac_f32_e32 v34, v112, v33
	v_cvt_pk_bf16_f32 v33, v32, v34
	ds_write_b32 v137, v33 offset:1632
	v_fma_f32 v33, -v113, v34, v39
	v_fmac_f32_e32 v33, v112, v32
	v_fma_f32 v32, v113, v32, v55
	v_fmac_f32_e32 v32, v112, v34
	v_cvt_pk_bf16_f32 v34, v33, v32
	ds_write_b32 v137, v34 offset:1904
	v_fma_f32 v34, -v113, v32, v40
	v_fmac_f32_e32 v34, v112, v33
	v_fma_f32 v33, v113, v33, v56
	v_fmac_f32_e32 v33, v112, v32
	v_cvt_pk_bf16_f32 v32, v34, v33
	ds_write_b32 v137, v32 offset:2176
	v_fma_f32 v32, -v113, v33, v41
	v_fmac_f32_e32 v32, v112, v34
	v_fma_f32 v34, v113, v34, v57
	v_fmac_f32_e32 v34, v112, v33
	v_cvt_pk_bf16_f32 v33, v32, v34
	ds_write_b32 v137, v33 offset:2448
	v_fma_f32 v33, -v113, v34, v42
	v_fmac_f32_e32 v33, v112, v32
	v_fma_f32 v32, v113, v32, v58
	v_fmac_f32_e32 v32, v112, v34
	v_cvt_pk_bf16_f32 v34, v33, v32
	ds_write_b32 v137, v34 offset:2720
	v_fma_f32 v34, -v113, v32, v43
	v_fmac_f32_e32 v34, v112, v33
	v_fma_f32 v33, v113, v33, v59
	v_fmac_f32_e32 v33, v112, v32
	v_cvt_pk_bf16_f32 v32, v34, v33
	ds_write_b32 v137, v32 offset:2992
	v_fma_f32 v32, -v113, v33, v44
	v_fmac_f32_e32 v32, v112, v34
	v_fma_f32 v34, v113, v34, v60
	v_fmac_f32_e32 v34, v112, v33
	v_cvt_pk_bf16_f32 v33, v32, v34
	ds_write_b32 v137, v33 offset:3264
	v_fma_f32 v33, -v113, v34, v45
	v_fmac_f32_e32 v33, v112, v32
	v_fma_f32 v32, v113, v32, v61
	v_fmac_f32_e32 v32, v112, v34
	v_cvt_pk_bf16_f32 v34, v33, v32
	ds_write_b32 v137, v34 offset:3536
	v_fma_f32 v34, -v113, v32, v46
	v_fmac_f32_e32 v34, v112, v33
	v_fma_f32 v33, v113, v33, v62
	v_fmac_f32_e32 v33, v112, v32
	v_cvt_pk_bf16_f32 v32, v34, v33
	ds_write_b32 v137, v32 offset:3808
	v_fma_f32 v32, -v113, v33, v47
	v_fmac_f32_e32 v32, v112, v34
	v_fmac_f32_e32 v63, v113, v34
	v_fmac_f32_e32 v63, v112, v33
	v_cvt_pk_bf16_f32 v32, v32, v63
	v_fma_f32 v33, 0, v117, v0
	ds_write_b32 v137, v32 offset:4080
	v_fmamk_f32 v32, v117, 0x80000000, v16
	v_fmac_f32_e32 v33, 0, v116
	v_fmac_f32_e32 v32, 0, v116
	v_fma_f32 v34, -v117, v33, v17
	v_fmac_f32_e32 v34, v116, v32
	v_fma_f32 v32, v117, v32, v1
	v_fmac_f32_e32 v32, v116, v33
	v_fma_f32 v33, -v117, v32, v18
	v_fmac_f32_e32 v33, v116, v34
	v_fma_f32 v34, v117, v34, v2
	v_fmac_f32_e32 v34, v116, v32
	v_fma_f32 v32, -v117, v34, v19
	v_fmac_f32_e32 v32, v116, v33
	v_fma_f32 v33, v117, v33, v3
	v_fmac_f32_e32 v33, v116, v34
	v_fma_f32 v34, -v117, v33, v20
	v_fmac_f32_e32 v34, v116, v32
	v_fma_f32 v32, v117, v32, v4
	v_fmac_f32_e32 v32, v116, v33
	v_fma_f32 v33, -v117, v32, v21
	v_fmac_f32_e32 v33, v116, v34
	v_fma_f32 v34, v117, v34, v5
	v_fmac_f32_e32 v34, v116, v32
	v_fma_f32 v32, -v117, v34, v22
	v_fmac_f32_e32 v32, v116, v33
	v_fma_f32 v33, v117, v33, v6
	v_fmac_f32_e32 v33, v116, v34
	v_fma_f32 v34, -v117, v33, v23
	v_fmac_f32_e32 v34, v116, v32
	v_fma_f32 v32, v117, v32, v7
	v_fmac_f32_e32 v32, v116, v33
	v_fma_f32 v33, -v117, v32, v24
	v_fmac_f32_e32 v33, v116, v34
	v_fma_f32 v34, v117, v34, v8
	v_fmac_f32_e32 v34, v116, v32
	v_fma_f32 v32, -v117, v34, v25
	v_fmac_f32_e32 v32, v116, v33
	v_fma_f32 v33, v117, v33, v9
	v_fmac_f32_e32 v33, v116, v34
	v_fma_f32 v34, -v117, v33, v26
	v_fmac_f32_e32 v34, v116, v32
	v_fma_f32 v32, v117, v32, v10
	v_fmac_f32_e32 v32, v116, v33
	v_fma_f32 v33, -v117, v32, v27
	v_fmac_f32_e32 v33, v116, v34
	v_fma_f32 v34, v117, v34, v11
	v_fmac_f32_e32 v34, v116, v32
	v_fma_f32 v32, -v117, v34, v28
	v_fmac_f32_e32 v32, v116, v33
	v_fma_f32 v33, v117, v33, v12
	v_fmac_f32_e32 v33, v116, v34
	v_fma_f32 v34, -v117, v33, v29
	v_fmac_f32_e32 v34, v116, v32
	v_fma_f32 v32, v117, v32, v13
	v_fmac_f32_e32 v32, v116, v33
	v_fma_f32 v33, -v117, v32, v30
	v_fmac_f32_e32 v33, v116, v34
	v_fma_f32 v34, v117, v34, v14
	v_fmac_f32_e32 v34, v116, v32
	v_fma_f32 v32, -v117, v34, v31
	v_fmac_f32_e32 v32, v116, v33
	v_fma_f32 v33, v117, v33, v15
	v_fmac_f32_e32 v33, v116, v34
	ds_bpermute_b32 v34, v149, v32
	ds_bpermute_b32 v35, v149, v33
	s_waitcnt lgkmcnt(1)
	v_cndmask_b32_e64 v32, v34, v32, s[0:1]
	s_waitcnt lgkmcnt(0)
	v_cndmask_b32_e64 v33, v35, v33, s[0:1]
	v_fma_f32 v32, -v231, v232, v32
	v_fmac_f32_e32 v33, v231, v233
	v_fmac_f32_e32 v32, v230, v233
	v_fmac_f32_e32 v33, v230, v232
	v_cndmask_b32_e64 v32, v32, v233, s[0:1]
	v_cndmask_b32_e64 v33, v33, v232, s[0:1]
	v_fma_f32 v16, -v117, v33, v16
	v_fma_f32 v0, v117, v32, v0
	v_fmac_f32_e32 v16, v116, v32
	v_fmac_f32_e32 v0, v116, v33
	v_fma_f32 v17, -v117, v0, v17
	v_fma_f32 v1, v117, v16, v1
	v_cvt_pk_bf16_f32 v32, v16, v0
	ds_write_b32 v137, v32 offset:128
	v_fmac_f32_e32 v17, v116, v16
	v_fmac_f32_e32 v1, v116, v0
	v_cvt_pk_bf16_f32 v0, v17, v1
	ds_write_b32 v137, v0 offset:400
	v_fma_f32 v0, -v117, v1, v18
	v_fma_f32 v2, v117, v17, v2
	v_fmac_f32_e32 v0, v116, v17
	v_fmac_f32_e32 v2, v116, v1
	v_cvt_pk_bf16_f32 v1, v0, v2
	ds_write_b32 v137, v1 offset:672
	v_fma_f32 v1, -v117, v2, v19
	v_fmac_f32_e32 v1, v116, v0
	v_fma_f32 v0, v117, v0, v3
	v_fmac_f32_e32 v0, v116, v2
	v_cvt_pk_bf16_f32 v2, v1, v0
	ds_write_b32 v137, v2 offset:944
	v_fma_f32 v2, -v117, v0, v20
	v_fmac_f32_e32 v2, v116, v1
	v_fma_f32 v1, v117, v1, v4
	v_fmac_f32_e32 v1, v116, v0
	v_cvt_pk_bf16_f32 v0, v2, v1
	ds_write_b32 v137, v0 offset:1216
	v_fma_f32 v0, -v117, v1, v21
	v_fmac_f32_e32 v0, v116, v2
	v_fma_f32 v2, v117, v2, v5
	v_fmac_f32_e32 v2, v116, v1
	v_cvt_pk_bf16_f32 v1, v0, v2
	ds_write_b32 v137, v1 offset:1488
	v_fma_f32 v1, -v117, v2, v22
	v_fmac_f32_e32 v1, v116, v0
	v_fma_f32 v0, v117, v0, v6
	v_fmac_f32_e32 v0, v116, v2
	v_cvt_pk_bf16_f32 v2, v1, v0
	ds_write_b32 v137, v2 offset:1760
	v_fma_f32 v2, -v117, v0, v23
	v_fmac_f32_e32 v2, v116, v1
	v_fma_f32 v1, v117, v1, v7
	v_fmac_f32_e32 v1, v116, v0
	v_cvt_pk_bf16_f32 v0, v2, v1
	ds_write_b32 v137, v0 offset:2032
	v_fma_f32 v0, -v117, v1, v24
	v_fmac_f32_e32 v0, v116, v2
	v_fma_f32 v2, v117, v2, v8
	v_fmac_f32_e32 v2, v116, v1
	v_cvt_pk_bf16_f32 v1, v0, v2
	ds_write_b32 v137, v1 offset:2304
	v_fma_f32 v1, -v117, v2, v25
	v_fmac_f32_e32 v1, v116, v0
	v_fma_f32 v0, v117, v0, v9
	v_fmac_f32_e32 v0, v116, v2
	v_cvt_pk_bf16_f32 v2, v1, v0
	ds_write_b32 v137, v2 offset:2576
	v_fma_f32 v2, -v117, v0, v26
	v_fmac_f32_e32 v2, v116, v1
	v_fma_f32 v1, v117, v1, v10
	v_fmac_f32_e32 v1, v116, v0
	v_cvt_pk_bf16_f32 v0, v2, v1
	ds_write_b32 v137, v0 offset:2848
	v_fma_f32 v0, -v117, v1, v27
	v_fmac_f32_e32 v0, v116, v2
	v_fma_f32 v2, v117, v2, v11
	v_fmac_f32_e32 v2, v116, v1
	v_cvt_pk_bf16_f32 v1, v0, v2
	ds_write_b32 v137, v1 offset:3120
	v_fma_f32 v1, -v117, v2, v28
	v_fmac_f32_e32 v1, v116, v0
	v_fma_f32 v0, v117, v0, v12
	v_fmac_f32_e32 v0, v116, v2
	v_cvt_pk_bf16_f32 v2, v1, v0
	ds_write_b32 v137, v2 offset:3392
	v_fma_f32 v2, -v117, v0, v29
	v_fmac_f32_e32 v2, v116, v1
	v_fma_f32 v1, v117, v1, v13
	v_fmac_f32_e32 v1, v116, v0
	v_cvt_pk_bf16_f32 v0, v2, v1
	ds_write_b32 v137, v0 offset:3664
	v_fma_f32 v0, -v117, v1, v30
	v_fmac_f32_e32 v0, v116, v2
	v_fma_f32 v2, v117, v2, v14
	v_fmac_f32_e32 v2, v116, v1
	v_cvt_pk_bf16_f32 v1, v0, v2
	ds_write_b32 v137, v1 offset:3936
	v_fma_f32 v1, -v117, v2, v31
	v_fmac_f32_e32 v15, v117, v0
	v_fmac_f32_e32 v1, v116, v0
	v_fmac_f32_e32 v15, v116, v2
	v_cvt_pk_bf16_f32 v0, v1, v15
	ds_write_b32 v137, v0 offset:4208
	ds_read_b128 v[0:3], v220
	ds_read_b128 v[4:7], v220 offset:64
	s_waitcnt lgkmcnt(1)
	v_mfma_f32_16x16x32_bf16 v[0:3], v[80:83], v[0:3], 0
	s_waitcnt lgkmcnt(0)
	v_mfma_f32_16x16x32_bf16 v[0:3], v[76:79], v[4:7], v[0:3]
	ds_read_b128 v[4:7], v220 offset:128
	s_waitcnt lgkmcnt(0)
	v_mfma_f32_16x16x32_bf16 v[0:3], v[72:75], v[4:7], v[0:3]
	ds_read_b128 v[4:7], v220 offset:192
	s_waitcnt lgkmcnt(0)
	v_mfma_f32_16x16x32_bf16 v[0:3], v[68:71], v[4:7], v[0:3]
	v_mov_b64_e32 v[4:5], v[252:253]
	s_nop 1
	v_lshlrev_b32_e32 v6, 16, v4
	v_and_b32_e32 v4, 0xffff0000, v4
	s_nop 2
	v_fma_f32 v1, v65, v4, v1
	v_mul_f32_e32 v4, 0x3d372713, v1
	v_mul_f32_e32 v4, v1, v4
	v_fma_f32 v4, v1, v4, v1
	v_mul_f32_e32 v4, 0x3f4c422a, v4
	v_add_f32_e32 v4, v4, v4
	v_mul_f32_e32 v4, 0x3fb8aa3b, v4
	v_exp_f32_e32 v4, v4
	v_fma_f32 v0, v64, v6, v0
	v_mul_f32_e32 v6, 0x3d372713, v0
	v_mul_f32_e32 v6, v0, v6
	v_add_f32_e32 v4, 1.0, v4
	v_rcp_f32_e32 v4, v4
	v_fma_f32 v6, v0, v6, v0
	v_mul_f32_e32 v6, 0x3f4c422a, v6
	v_add_f32_e32 v6, v6, v6
	v_sub_f32_e32 v4, 1.0, v4
	v_mul_f32_e32 v1, v1, v4
	v_lshlrev_b32_e32 v4, 16, v5
	v_fma_f32 v2, v66, v4, v2
	v_mul_f32_e32 v4, 0x3d372713, v2
	v_mul_f32_e32 v4, v2, v4
	v_fma_f32 v4, v2, v4, v2
	v_mul_f32_e32 v4, 0x3f4c422a, v4
	v_add_f32_e32 v4, v4, v4
	v_mul_f32_e32 v4, 0x3fb8aa3b, v4
	v_exp_f32_e32 v4, v4
	v_mul_f32_e32 v6, 0x3fb8aa3b, v6
	v_exp_f32_e32 v6, v6
	v_add_f32_e32 v4, 1.0, v4
	v_rcp_f32_e32 v4, v4
	v_add_f32_e32 v6, 1.0, v6
	v_rcp_f32_e32 v6, v6
	v_sub_f32_e32 v4, 1.0, v4
	v_mul_f32_e32 v2, v2, v4
	v_and_b32_e32 v4, 0xffff0000, v5
	v_fmac_f32_e32 v3, v67, v4
	v_mul_f32_e32 v4, 0x3d372713, v3
	v_mul_f32_e32 v4, v3, v4
	v_fma_f32 v4, v3, v4, v3
	v_mul_f32_e32 v4, 0x3f4c422a, v4
	v_add_f32_e32 v4, v4, v4
	v_mul_f32_e32 v4, 0x3fb8aa3b, v4
	v_exp_f32_e32 v4, v4
	v_sub_f32_e32 v6, 1.0, v6
	v_mul_f32_e32 v0, v0, v6
	v_cvt_pk_bf16_f32 v0, v0, v1
	v_add_f32_e32 v4, 1.0, v4
	v_rcp_f32_e32 v4, v4
	s_nop 0
	v_sub_f32_e32 v4, 1.0, v4
	v_mul_f32_e32 v3, v3, v4
	v_cvt_pk_bf16_f32 v1, v2, v3
	ds_write_b64 v236, v[0:1] offset:33280
	ds_read_b128 v[0:3], v220 offset:4352
	ds_read_b128 v[4:7], v220 offset:4416
	s_waitcnt lgkmcnt(1)
	v_mfma_f32_16x16x32_bf16 v[0:3], v[80:83], v[0:3], 0
	s_waitcnt lgkmcnt(0)
	v_mfma_f32_16x16x32_bf16 v[0:3], v[76:79], v[4:7], v[0:3]
	ds_read_b128 v[4:7], v220 offset:4480
	s_waitcnt lgkmcnt(0)
	v_mfma_f32_16x16x32_bf16 v[0:3], v[72:75], v[4:7], v[0:3]
	ds_read_b128 v[4:7], v220 offset:4544
	s_waitcnt lgkmcnt(0)
	v_mfma_f32_16x16x32_bf16 v[0:3], v[68:71], v[4:7], v[0:3]
	v_mov_b64_e32 v[4:5], v[242:243]
	s_nop 1
	v_lshlrev_b32_e32 v6, 16, v4
	v_and_b32_e32 v4, 0xffff0000, v4
	s_nop 2
	v_fma_f32 v1, v65, v4, v1
	v_mul_f32_e32 v4, 0x3d372713, v1
	v_mul_f32_e32 v4, v1, v4
	v_fma_f32 v4, v1, v4, v1
	v_mul_f32_e32 v4, 0x3f4c422a, v4
	v_add_f32_e32 v4, v4, v4
	v_mul_f32_e32 v4, 0x3fb8aa3b, v4
	v_exp_f32_e32 v4, v4
	v_fma_f32 v0, v64, v6, v0
	v_mul_f32_e32 v6, 0x3d372713, v0
	v_mul_f32_e32 v6, v0, v6
	v_add_f32_e32 v4, 1.0, v4
	v_rcp_f32_e32 v4, v4
	v_fma_f32 v6, v0, v6, v0
	v_mul_f32_e32 v6, 0x3f4c422a, v6
	v_add_f32_e32 v6, v6, v6
	v_sub_f32_e32 v4, 1.0, v4
	v_mul_f32_e32 v1, v1, v4
	v_lshlrev_b32_e32 v4, 16, v5
	v_fma_f32 v2, v66, v4, v2
	v_mul_f32_e32 v4, 0x3d372713, v2
	v_mul_f32_e32 v4, v2, v4
	v_fma_f32 v4, v2, v4, v2
	v_mul_f32_e32 v4, 0x3f4c422a, v4
	v_add_f32_e32 v4, v4, v4
	v_mul_f32_e32 v4, 0x3fb8aa3b, v4
	v_exp_f32_e32 v4, v4
	v_mul_f32_e32 v6, 0x3fb8aa3b, v6
	v_exp_f32_e32 v6, v6
	v_add_f32_e32 v4, 1.0, v4
	v_rcp_f32_e32 v4, v4
	v_add_f32_e32 v6, 1.0, v6
	v_rcp_f32_e32 v6, v6
	v_sub_f32_e32 v4, 1.0, v4
	v_mul_f32_e32 v2, v2, v4
	v_and_b32_e32 v4, 0xffff0000, v5
	v_fmac_f32_e32 v3, v67, v4
	v_mul_f32_e32 v4, 0x3d372713, v3
	v_mul_f32_e32 v4, v3, v4
	v_fma_f32 v4, v3, v4, v3
	v_mul_f32_e32 v4, 0x3f4c422a, v4
	v_add_f32_e32 v4, v4, v4
	v_mul_f32_e32 v4, 0x3fb8aa3b, v4
	v_exp_f32_e32 v4, v4
	v_sub_f32_e32 v6, 1.0, v6
	v_mul_f32_e32 v0, v0, v6
	v_cvt_pk_bf16_f32 v0, v0, v1
	v_add_f32_e32 v4, 1.0, v4
	v_rcp_f32_e32 v4, v4
	s_nop 0
	v_sub_f32_e32 v4, 1.0, v4
	v_mul_f32_e32 v3, v3, v4
	v_cvt_pk_bf16_f32 v1, v2, v3
	v_add_u32_e32 v2, v132, v155
	ds_write_b64 v2, v[0:1]
	s_cbranch_vccnz .LBB0_405
	s_waitcnt lgkmcnt(0)
	s_barrier
	global_load_dwordx4 v[68:71], v[156:157], off
	global_load_dwordx4 v[40:43], v[156:157], off offset:1024
	global_load_dwordx4 v[76:79], v[156:157], off offset:2048
	global_load_dwordx4 v[88:91], v[156:157], off offset:3072
	global_load_dwordx4 v[32:35], v[158:159], off
	global_load_dwordx4 v[36:39], v[160:161], off
	global_load_dwordx4 v[44:47], v[162:163], off
	global_load_dwordx4 v[80:83], v[164:165], off
	global_load_dwordx4 v[72:75], v[166:167], off
	global_load_dwordx4 v[84:87], v[168:169], off
	global_load_dwordx4 v[92:95], v[170:171], off
	global_load_dwordx4 v[96:99], v[172:173], off
	v_mov_b32_e32 v0, 0
	s_mov_b32 s6, -4
	v_mov_b32_e32 v132, v219
	v_mov_b32_e32 v224, v218
	v_mov_b64_e32 v[194:195], v[174:175]
	v_mov_b32_e32 v1, v0
	v_mov_b32_e32 v2, v0
	v_mov_b32_e32 v3, v0
	v_mov_b32_e32 v8, v0
	v_mov_b32_e32 v9, v0
	v_mov_b32_e32 v10, v0
	v_mov_b32_e32 v11, v0
	v_mov_b32_e32 v4, v0
	v_mov_b32_e32 v5, v0
	v_mov_b32_e32 v6, v0
	v_mov_b32_e32 v7, v0
	v_mov_b32_e32 v12, v0
	v_mov_b32_e32 v13, v0
	v_mov_b32_e32 v14, v0
	v_mov_b32_e32 v15, v0
	v_mov_b32_e32 v16, v0
	v_mov_b32_e32 v17, v0
	v_mov_b32_e32 v18, v0
	v_mov_b32_e32 v19, v0
	v_mov_b32_e32 v20, v0
	v_mov_b32_e32 v21, v0
	v_mov_b32_e32 v22, v0
	v_mov_b32_e32 v23, v0
	v_mov_b32_e32 v24, v0
	v_mov_b32_e32 v25, v0
	v_mov_b32_e32 v26, v0
	v_mov_b32_e32 v27, v0
	v_mov_b32_e32 v28, v0
	v_mov_b32_e32 v29, v0
	v_mov_b32_e32 v30, v0
	v_mov_b32_e32 v31, v0
	v_mov_b32_e32 v48, v0
	v_mov_b32_e32 v49, v0
	v_mov_b32_e32 v50, v0
	v_mov_b32_e32 v51, v0
	v_mov_b32_e32 v52, v0
	v_mov_b32_e32 v53, v0
	v_mov_b32_e32 v54, v0
	v_mov_b32_e32 v55, v0
	v_mov_b32_e32 v56, v0
	v_mov_b32_e32 v57, v0
	v_mov_b32_e32 v58, v0
	v_mov_b32_e32 v59, v0
	v_mov_b32_e32 v60, v0
	v_mov_b32_e32 v61, v0
	v_mov_b32_e32 v62, v0
	v_mov_b32_e32 v63, v0
	v_mov_b32_e32 v64, v0
	v_mov_b32_e32 v65, v0
	v_mov_b32_e32 v66, v0
	v_mov_b32_e32 v67, v0
	v_mov_b32_e32 v100, v0
	v_mov_b32_e32 v101, v0
	v_mov_b32_e32 v102, v0
	v_mov_b32_e32 v103, v0
	v_mov_b32_e32 v104, v0
	v_mov_b32_e32 v105, v0
	v_mov_b32_e32 v106, v0
	v_mov_b32_e32 v107, v0
	v_mov_b32_e32 v108, v0
	v_mov_b32_e32 v109, v0
	v_mov_b32_e32 v110, v0
	v_mov_b32_e32 v111, v0
	s_branch .LBB0_408

.LBB0_597:
	s_cmp_gt_i32 s29, 6
	s_cselect_b64 s[4:5], -1, 0
	s_and_b64 s[6:7], s[12:13], s[4:5]
	s_andn2_b64 vcc, exec, s[6:7]
	s_cbranch_vccnz .LBB0_647
	s_waitcnt vmcnt(0)
	v_cmp_eq_u32_e32 vcc, 0, v196
	s_waitcnt lgkmcnt(0)
	s_barrier
	s_and_saveexec_b64 s[6:7], vcc
	s_cbranch_execz .LBB0_646
	s_add_i32 s8, s30, -1
	s_cmp_lg_u32 s2, s8
	s_cbranch_scc1 .Ltok_nobump
	v_mov_b32_e32 v0, 0
	v_mov_b32_e32 v1, 0x10000
	global_atomic_add v0, v1, s[98:99] offset:32
.Ltok_nobump:
	v_mov_b32_e32 v0, s94
	s_waitcnt vmcnt(0) expcnt(0) lgkmcnt(0)
	ds_read_b32 v2, v0
	ds_read_b32 v0, v0 offset:4
	s_waitcnt lgkmcnt(1)
	v_cmp_ne_u32_e32 vcc, 0, v2
	s_cbranch_vccnz .LBB0_614
	s_add_u32 s8, s70, 0x4200
	s_addc_u32 s9, s71, 0
	s_add_u32 s12, s70, 0x4400
	s_addc_u32 s13, s71, 0
	s_add_u32 s14, s70, 0x4500
	s_addc_u32 s15, s71, 0
	s_add_u32 s16, s70, 0x4600
	s_addc_u32 s17, s71, 0
	s_add_u32 s18, s70, 0x4700
	s_addc_u32 s19, s71, 0
	s_add_u32 s20, s70, 0x4800
	s_addc_u32 s21, s71, 0
	s_add_u32 s26, s70, 0x4900
	s_addc_u32 s27, s71, 0
	s_add_u32 s34, s70, 0x4a00
	s_addc_u32 s35, s71, 0
	s_add_u32 s36, s70, 0x4b00
	s_addc_u32 s37, s71, 0
	s_add_u32 s38, s70, 0x4c00
	s_addc_u32 s39, s71, 0
	s_add_u32 s40, s70, 0x4d00
	s_addc_u32 s41, s71, 0
	s_add_u32 s42, s70, 0x4e00
	s_addc_u32 s43, s71, 0
	s_add_u32 s44, s70, 0x4f00
	s_addc_u32 s45, s71, 0
	s_add_u32 s46, s70, 0x5000
	s_addc_u32 s47, s71, 0
	s_add_u32 s48, s70, 0x5100
	s_addc_u32 s49, s71, 0
	s_add_u32 s50, s70, 0x5200
	s_addc_u32 s51, s71, 0
	s_mul_i32 s3, s31, s95
	s_add_u32 s52, s70, 0x5300
	s_mul_i32 s3, s3, s30
	s_addc_u32 s53, s71, 0
	s_mov_b32 s10, 1
	v_mov_b32_e32 v16, 0
	s_branch .LBB0_602

	.amdhsa_kernel _Z10fwd_kernel4Args
		.amdhsa_group_segment_fixed_size 0
		.amdhsa_private_segment_fixed_size 0
		.amdhsa_kernarg_size 472
		.amdhsa_user_sgpr_count 2
		.amdhsa_user_sgpr_dispatch_ptr 0
		.amdhsa_user_sgpr_queue_ptr 0
		.amdhsa_user_sgpr_kernarg_segment_ptr 1
		.amdhsa_user_sgpr_dispatch_id 0
		.amdhsa_user_sgpr_kernarg_preload_length 0
		.amdhsa_user_sgpr_kernarg_preload_offset 0
		.amdhsa_user_sgpr_private_segment_size 0
		.amdhsa_uses_dynamic_stack 0
		.amdhsa_enable_private_segment 0
		.amdhsa_system_sgpr_workgroup_id_x 1
		.amdhsa_system_sgpr_workgroup_id_y 0
		.amdhsa_system_sgpr_workgroup_id_z 0
		.amdhsa_system_sgpr_workgroup_info 0
		.amdhsa_system_vgpr_workitem_id 2
		.amdhsa_next_free_vgpr 256
		.amdhsa_next_free_sgpr 102
		.amdhsa_accum_offset 256
		.amdhsa_reserve_vcc 1
		.amdhsa_float_round_mode_32 0
		.amdhsa_float_round_mode_16_64 0
		.amdhsa_float_denorm_mode_32 3
		.amdhsa_float_denorm_mode_16_64 3
		.amdhsa_dx10_clamp 1
		.amdhsa_ieee_mode 1
		.amdhsa_fp16_overflow 0
		.amdhsa_tg_split 0
		.amdhsa_exception_fp_ieee_invalid_op 0
		.amdhsa_exception_fp_denorm_src 0
		.amdhsa_exception_fp_ieee_div_zero 0
		.amdhsa_exception_fp_ieee_overflow 0
		.amdhsa_exception_fp_ieee_underflow 0
		.amdhsa_exception_fp_ieee_inexact 0
		.amdhsa_exception_int_div_zero 0
	.end_amdhsa_kernel

amdhsa.kernels:
  - .agpr_count:     0
    .args:
      - .offset:         0
        .size:           216
        .value_kind:     by_value
      - .offset:         216
        .size:           4
        .value_kind:     hidden_block_count_x
      - .offset:         220
        .size:           4
        .value_kind:     hidden_block_count_y
      - .offset:         224
        .size:           4
        .value_kind:     hidden_block_count_z
      - .offset:         228
        .size:           2
        .value_kind:     hidden_group_size_x
      - .offset:         230
        .size:           2
        .value_kind:     hidden_group_size_y
      - .offset:         232
        .size:           2
        .value_kind:     hidden_group_size_z
      - .offset:         234
        .size:           2
        .value_kind:     hidden_remainder_x
      - .offset:         236
        .size:           2
        .value_kind:     hidden_remainder_y
      - .offset:         238
        .size:           2
        .value_kind:     hidden_remainder_z
      - .offset:         256
        .size:           8
        .value_kind:     hidden_global_offset_x
      - .offset:         264
        .size:           8
        .value_kind:     hidden_global_offset_y
      - .offset:         272
        .size:           8
        .value_kind:     hidden_global_offset_z
      - .offset:         280
        .size:           2
        .value_kind:     hidden_grid_dims
      - .offset:         304
        .size:           8
        .value_kind:     hidden_multigrid_sync_arg
      - .offset:         336
        .size:           4
        .value_kind:     hidden_dynamic_lds_size
    .group_segment_fixed_size: 0
    .kernarg_segment_align: 8
    .kernarg_segment_size: 472
    .language:       OpenCL C
    .language_version:
      - 2
      - 0
    .max_flat_workgroup_size: 512
    .name:           _Z10fwd_kernel4Args
    .private_segment_fixed_size: 0
    .sgpr_count:     108
    .sgpr_spill_count: 9
    .symbol:         _Z10fwd_kernel4Args.kd
    .uniform_work_group_size: 1
    .uses_dynamic_stack: false
    .vgpr_count:     256
    .vgpr_spill_count: 0
    .wavefront_size: 64
